# P4 ssd_s3: next head's start state fetched at head start by LDS-DMA into spare LDS (was a late global load with an exposed HBM round trip per head)
# baseline (speedup 1.0000x reference)
.LBB0_530:
	s_ashr_i32 s16, s38, 5
	s_bfe_u32 s20, s38, 0x40001
	s_ashr_i32 s17, s16, 31
	s_and_b32 s4, s38, 1
	s_lshl_b64 s[18:19], s[16:17], 11
	s_lshl_b32 s22, s20, 7
	s_lshl_b64 s[16:17], s[16:17], 8
	s_lshl_b32 s20, s20, 4
	s_or_b32 s39, s16, s20
	s_lshl_b32 s40, s4, 3
	v_mov_b32_e32 v146, v0
	s_or_b32 s16, s39, s40
	s_or_b32 s18, s18, s22
	v_ashrrev_i32_e32 v150, 3, v146
	s_lshl_b64 s[20:21], s[16:17], 15
	v_lshlrev_b32_e32 v2, 4, v146
	s_add_u32 s20, s74, s20
	s_waitcnt vmcnt(5)
	v_lshlrev_b32_e32 v42, 7, v150
	v_and_b32_e32 v149, 0x70, v2
	s_addc_u32 s21, s75, s21
	v_ashrrev_i32_e32 v43, 31, v42
	v_lshl_add_u64 v[2:3], v[42:43], 2, s[20:21]
	v_lshlrev_b32_e32 v74, 2, v149
	v_lshl_add_u64 v[14:15], v[2:3], 0, v[74:75]
	s_add_u32 s96, s20, 0x10000
	s_addc_u32 s97, s21, 0
	v_readfirstlane_b32 s98, v0
	v_lshrrev_b32_e32 v239, 3, v0
	v_and_b32_e32 v240, 7, v0
	s_lshr_b32 s98, s98, 6
	s_lshl_b32 s98, s98, 12
	s_add_i32 s98, s98, 0x11000
	v_lshlrev_b32_e32 v239, 9, v239
	v_lshl_or_b32 v239, v240, 6, v239
	v_and_b32_e32 v240, 63, v0
	v_lshlrev_b32_e32 v240, 4, v240
	v_add_u32_e32 v240, s98, v240
	global_load_dwordx4 v[2:5], v[14:15], off offset:48
	global_load_dwordx4 v[6:9], v[14:15], off offset:32
	global_load_dwordx4 v[10:13], v[14:15], off offset:16
	s_nop 0
	global_load_dwordx4 v[14:17], v[14:15], off
	v_lshlrev_b32_e32 v18, 3, v146
	v_ashrrev_i32_e32 v151, 2, v146
	v_and_b32_e32 v152, 0x78, v18
	s_waitcnt vmcnt(8)
	v_and_b32_e32 v46, -4, v151
	v_lshl_or_b32 v18, s4, 7, v152
	v_or_b32_e32 v22, 0x500, v18
	v_ashrrev_i32_e32 v47, 31, v46
	v_add_u32_e32 v23, s22, v46
	v_lshl_add_u64 v[20:21], s[18:19], 0, v[46:47]
	v_cmp_lt_i32_e32 vcc, 2, v23
	v_lshlrev_b32_e32 v18, 1, v22
	v_mov_b32_e32 v49, 0
	v_mov_b32_e32 v57, 0
	v_mov_b32_e32 v67, 0
	v_mov_b32_e32 v77, 0
	v_mov_b32_e32 v89, 0
	v_mov_b32_e32 v97, 0
	v_mov_b32_e32 v103, 0
	v_mov_b32_e32 v111, 0
	s_barrier
	v_mov_b32_e32 v244, 0
	v_mov_b32_e32 v245, 0
	v_mov_b32_e32 v246, 0
	v_mov_b32_e32 v247, 0
	s_and_saveexec_b64 s[22:23], vcc
	s_cbranch_execz .LBB0_532
	v_mov_b64_e32 v[24:25], s[2:3]
	v_mad_u64_u32 v[24:25], s[42:43], v20, s28, v[24:25]
	v_mov_b32_e32 v26, v25
	v_mad_u64_u32 v[26:27], s[42:43], v21, s28, v[26:27]
	v_mov_b32_e32 v25, v26
	v_mov_b32_e32 v19, v75
	v_lshl_add_u64 v[24:25], v[24:25], 0, v[18:19]
	v_add_co_u32_e32 v24, vcc, 0xffffa000, v24
	s_nop 1
	v_addc_co_u32_e32 v25, vcc, -1, v25, vcc
	global_load_dwordx4 v[244:247], v[24:25], off offset:-3072

.LBB0_544:
	s_or_b64 exec, exec, s[22:23]
	s_waitcnt vmcnt(0)
	v_lshlrev_b32_e32 v111, 16, v244
	v_and_b32_e32 v103, 0xffff0000, v244
	v_lshlrev_b32_e32 v97, 16, v245
	v_and_b32_e32 v89, 0xffff0000, v245
	v_lshlrev_b32_e32 v77, 16, v246
	v_and_b32_e32 v67, 0xffff0000, v246
	v_lshlrev_b32_e32 v57, 16, v247
	v_and_b32_e32 v49, 0xffff0000, v247
	v_lshlrev_b32_e32 v110, 16, v248
	v_and_b32_e32 v102, 0xffff0000, v248
	v_lshlrev_b32_e32 v96, 16, v249
	v_and_b32_e32 v88, 0xffff0000, v249
	v_lshlrev_b32_e32 v76, 16, v250
	v_and_b32_e32 v66, 0xffff0000, v250
	v_lshlrev_b32_e32 v56, 16, v251
	v_and_b32_e32 v48, 0xffff0000, v251
	v_lshlrev_b32_e32 v69, 16, v252
	v_and_b32_e32 v95, 0xffff0000, v252
	v_lshlrev_b32_e32 v87, 16, v253
	v_and_b32_e32 v81, 0xffff0000, v253
	v_lshlrev_b32_e32 v71, 16, v254
	v_and_b32_e32 v61, 0xffff0000, v254
	v_lshlrev_b32_e32 v55, 16, v255
	v_and_b32_e32 v51, 0xffff0000, v255
	v_lshlrev_b32_e32 v68, 16, v128
	v_and_b32_e32 v94, 0xffff0000, v128
	v_lshlrev_b32_e32 v86, 16, v129
	v_and_b32_e32 v80, 0xffff0000, v129
	v_lshlrev_b32_e32 v70, 16, v130
	v_and_b32_e32 v60, 0xffff0000, v130
	v_lshlrev_b32_e32 v54, 16, v131
	v_and_b32_e32 v50, 0xffff0000, v131
	v_lshlrev_b32_e32 v62, 16, v132
	v_and_b32_e32 v90, 0xffff0000, v132
	v_lshlrev_b32_e32 v82, 16, v133
	v_and_b32_e32 v72, 0xffff0000, v133
	v_lshlrev_b32_e32 v64, 16, v134
	v_and_b32_e32 v58, 0xffff0000, v134
	v_lshlrev_b32_e32 v52, 16, v135
	v_and_b32_e32 v44, 0xffff0000, v135
	v_lshlrev_b32_e32 v118, 16, v136
	v_and_b32_e32 v112, 0xffff0000, v136
	v_lshlrev_b32_e32 v106, 16, v137
	v_and_b32_e32 v100, 0xffff0000, v137
	v_lshlrev_b32_e32 v98, 16, v138
	v_and_b32_e32 v92, 0xffff0000, v138
	v_lshlrev_b32_e32 v84, 16, v139
	v_and_b32_e32 v78, 0xffff0000, v139
	v_lshlrev_b32_e32 v116, 16, v140
	v_and_b32_e32 v126, 0xffff0000, v140
	v_lshlrev_b32_e32 v124, 16, v141
	v_and_b32_e32 v122, 0xffff0000, v141
	v_lshlrev_b32_e32 v120, 16, v142
	v_and_b32_e32 v114, 0xffff0000, v142
	v_lshlrev_b32_e32 v108, 16, v143
	v_and_b32_e32 v104, 0xffff0000, v143
	v_readlane_b32 s80, v242, 2
	v_readlane_b32 s84, v242, 6
	v_readlane_b32 s85, v242, 7
	v_lshlrev_b32_e32 v26, 2, v22
	v_mov_b32_e32 v27, v75
	v_readlane_b32 s86, v242, 8
	v_readlane_b32 s87, v242, 9
	s_mov_b64 s[44:45], s[84:85]
	v_lshl_add_u64 v[22:23], s[44:45], 0, v[26:27]
	v_add_co_u32_e32 v24, vcc, s30, v22
	global_load_dwordx4 v[18:21], v26, s[44:45] offset:16
	global_load_dwordx4 v[30:33], v26, s[44:45]
	v_addc_co_u32_e32 v25, vcc, 0, v23, vcc
	global_load_dwordx4 v[140:143], v[24:25], off offset:2048
	v_add_co_u32_e32 v24, vcc, s31, v22
	s_mov_b64 s[46:47], s[86:87]
	s_nop 0
	v_addc_co_u32_e32 v25, vcc, 0, v23, vcc
	v_add_co_u32_e32 v28, vcc, s29, v22
	v_mov_b32_e32 v91, v94
	s_nop 0
	v_addc_co_u32_e32 v29, vcc, 0, v23, vcc
	global_load_dwordx4 v[154:157], v[28:29], off offset:2048
	global_load_dwordx4 v[34:37], v[24:25], off
	v_lshl_add_u64 v[24:25], v[22:23], 0, s[8:9]
	global_load_dwordx4 v[158:161], v[24:25], off offset:16
	v_lshl_add_u64 v[24:25], v[22:23], 0, s[10:11]
	v_lshl_add_u64 v[22:23], v[22:23], 0, s[12:13]
	global_load_dwordx4 v[162:165], v[22:23], off offset:16
	s_nop 0
	global_load_dwordx4 v[22:25], v[24:25], off offset:16
	s_nop 0
	global_load_dwordx4 v[38:41], v26, s[46:47]
	s_nop 0
	global_load_dwordx4 v[26:29], v26, s[46:47] offset:16
	v_mov_b32_e32 v83, v86
	v_mov_b32_e32 v119, v62
	v_mov_b32_e32 v113, v90
	v_mov_b32_e32 v107, v82
	v_mov_b32_e32 v101, v72
	v_mov_b32_e32 v99, v64
	v_mov_b32_e32 v93, v58
	v_mov_b32_e32 v127, v112
	v_mov_b32_e32 v117, v118
	v_mov_b32_e32 v125, v106
	v_mov_b32_e32 v123, v100
	v_mov_b32_e32 v121, v98
	v_mov_b32_e32 v115, v92
	v_mov_b32_e32 v109, v84
	v_mov_b32_e32 v105, v78
	v_and_b32_e32 v147, 15, v146
	v_bfe_u32 v148, v146, 4, 2
	s_waitcnt vmcnt(12)
	v_cvt_pk_bf16_f32 v6, v6, v7
	v_cvt_pk_bf16_f32 v7, v8, v9
	v_cvt_pk_bf16_f32 v8, v2, v3
	v_lshlrev_b32_e32 v2, 1, v149
	s_waitcnt vmcnt(10)
	v_cvt_pk_bf16_f32 v14, v14, v15
	v_cvt_pk_bf16_f32 v15, v16, v17
	v_cvt_pk_bf16_f32 v16, v10, v11
	v_cvt_pk_bf16_f32 v17, v12, v13
	v_cvt_pk_bf16_f32 v9, v4, v5
	v_readlane_b32 s81, v242, 3
	v_readlane_b32 s82, v242, 4
	v_readlane_b32 s83, v242, 5
	v_readlane_b32 s88, v242, 10
	v_readlane_b32 s89, v242, 11
	v_readlane_b32 s90, v242, 12
	v_readlane_b32 s91, v242, 13
	v_readlane_b32 s92, v242, 14
	v_readlane_b32 s93, v242, 15
	v_readlane_b32 s94, v242, 16
	v_readlane_b32 s95, v242, 17
	s_waitcnt vmcnt(9)
	v_mov_b32_e32 v133, v18
	s_waitcnt vmcnt(8)
	v_mov_b32_e32 v129, v30
	v_mov_b32_e32 v131, v32
	s_waitcnt vmcnt(7)
	v_mov_b32_e32 v128, v140
	v_mov_b32_e32 v30, v141
	v_mov_b32_e32 v130, v142
	v_pk_mul_f32 v[140:141], v[110:111], v[128:129]
	v_mov_b32_e32 v32, v143
	v_pk_mul_f32 v[168:169], v[88:89], v[32:33]
	s_waitcnt vmcnt(6)
	v_mov_b32_e32 v138, v154
	s_waitcnt vmcnt(5)
	v_mov_b32_e32 v139, v34
	v_mov_b32_e32 v34, v155
	s_waitcnt vmcnt(4)
	v_mov_b32_e32 v132, v158
	s_waitcnt vmcnt(2)
	v_mov_b32_e32 v135, v22
	v_mov_b32_e32 v18, v159
	v_pk_mul_f32 v[158:159], v[96:97], v[130:131]
	s_waitcnt vmcnt(1)
	v_add_f32_e32 v22, v141, v38
	v_mov_b32_e32 v136, v156
	v_mov_b32_e32 v137, v36
	v_pk_mul_f32 v[142:143], v[68:69], v[138:139]
	v_pk_mul_f32 v[154:155], v[102:103], v[30:31]
	v_add_f32_e32 v47, v159, v40
	v_add_f32_e32 v22, v140, v22
	v_pk_mul_f32 v[166:167], v[86:87], v[136:137]
	v_add_f32_e32 v45, v155, v39
	v_add_f32_e32 v47, v158, v47
	v_add_f32_e32 v22, v143, v22
	v_mov_b32_e32 v36, v157
	v_pk_mul_f32 v[156:157], v[94:95], v[34:35]
	v_add_f32_e32 v45, v154, v45
	v_add_f32_e32 v47, v167, v47
	v_add_f32_e32 v22, v142, v22
	v_add_f32_e32 v45, v157, v45
	v_add_f32_e32 v65, v166, v47
	v_mul_f32_e32 v47, 0xbfb8aa3b, v22
	v_add_f32_e32 v45, v156, v45
	v_exp_f32_e32 v47, v47
	v_pk_mul_f32 v[176:177], v[66:67], v[18:19]
	v_mul_f32_e32 v67, 0xbfb8aa3b, v45
	v_exp_f32_e32 v67, v67
	v_add_f32_e32 v47, 1.0, v47
	v_rcp_f32_e32 v47, v47
	s_waitcnt vmcnt(0)
	v_add_f32_e32 v63, v177, v27
	v_add_f32_e32 v67, 1.0, v67
	v_rcp_f32_e32 v67, v67
	v_mul_f32_e32 v47, v22, v47
	v_mov_b32_e32 v22, v163
	v_add_f32_e32 v63, v176, v63
	v_pk_mul_f32 v[140:141], v[60:61], v[22:23]
	v_mul_f32_e32 v67, v45, v67
	v_add_f32_e32 v45, v141, v63
	v_add_f32_e32 v45, v140, v45
	v_mov_b32_e32 v140, v160
	v_mov_b32_e32 v141, v20
	v_pk_mul_f32 v[142:143], v[56:57], v[140:141]
	v_mul_f32_e32 v63, 0xbfb8aa3b, v45
	v_add_f32_e32 v20, v143, v28
	v_exp_f32_e32 v63, v63
	v_add_f32_e32 v20, v142, v20
	v_mov_b32_e32 v142, v164
	v_mov_b32_e32 v143, v24
	v_pk_mul_f32 v[154:155], v[54:55], v[142:143]
	v_pk_mul_f32 v[172:173], v[76:77], v[132:133]
	v_mul_f32_e32 v73, 0xbfb8aa3b, v65
	v_add_f32_e32 v20, v155, v20
	v_mov_b32_e32 v134, v162
	v_add_f32_e32 v53, v169, v41
	v_add_f32_e32 v59, v173, v26
	v_exp_f32_e32 v73, v73
	v_add_f32_e32 v57, v154, v20
	v_pk_mul_f32 v[170:171], v[80:81], v[36:37]
	v_pk_mul_f32 v[174:175], v[70:71], v[134:135]
	v_add_f32_e32 v53, v168, v53
	v_add_f32_e32 v59, v172, v59
	v_add_f32_e32 v63, 1.0, v63
	v_mul_f32_e32 v20, 0xbfb8aa3b, v57
	v_add_f32_e32 v53, v171, v53
	v_add_f32_e32 v59, v175, v59
	v_rcp_f32_e32 v63, v63
	v_exp_f32_e32 v20, v20
	v_add_f32_e32 v53, v170, v53
	v_add_f32_e32 v59, v174, v59
	v_mul_f32_e32 v77, 0xbfb8aa3b, v53
	v_mul_f32_e32 v79, 0xbfb8aa3b, v59
	v_add_f32_e32 v73, 1.0, v73
	v_exp_f32_e32 v77, v77
	v_exp_f32_e32 v79, v79
	v_rcp_f32_e32 v73, v73
	v_mul_f32_e32 v155, v45, v63
	v_add_f32_e32 v45, 1.0, v20
	v_mov_b32_e32 v20, v161
	v_pk_mul_f32 v[156:157], v[48:49], v[20:21]
	v_add_f32_e32 v77, 1.0, v77
	v_add_f32_e32 v24, v157, v29
	v_mul_f32_e32 v103, v65, v73
	v_add_f32_e32 v73, 1.0, v79
	v_add_f32_e32 v49, v156, v24
	v_mov_b32_e32 v24, v165
	v_rcp_f32_e32 v65, v77
	v_rcp_f32_e32 v73, v73
	v_pk_mul_f32 v[156:157], v[50:51], v[24:25]
	v_mov_b32_e32 v63, v68
	v_add_f32_e32 v49, v157, v49
	v_add_f32_e32 v49, v156, v49
	v_mov_b32_e32 v156, v69
	v_mov_b32_e32 v157, v110
	v_pk_mul_f32 v[110:111], v[156:157], v[128:129]
	v_mul_f32_e32 v153, v53, v65
	v_mul_f32_e32 v154, v59, v73
	v_mul_f32_e32 v53, 0xbfb8aa3b, v49
	v_add_f32_e32 v59, v111, v38
	v_exp_f32_e32 v53, v53
	v_add_f32_e32 v59, v110, v59
	v_pk_mul_f32 v[110:111], v[62:63], v[138:139]
	v_rcp_f32_e32 v45, v45
	v_add_f32_e32 v59, v111, v59
	v_add_f32_e32 v59, v110, v59
	v_mov_b32_e32 v110, v95
	v_mov_b32_e32 v111, v102
	v_pk_mul_f32 v[110:111], v[110:111], v[30:31]
	v_mul_f32_e32 v65, 0xbfb8aa3b, v59
	v_add_f32_e32 v53, 1.0, v53
	v_add_f32_e32 v73, v111, v39
	v_exp_f32_e32 v65, v65
	v_rcp_f32_e32 v53, v53
	v_add_f32_e32 v73, v110, v73
	v_pk_mul_f32 v[110:111], v[90:91], v[34:35]
	v_add_f32_e32 v65, 1.0, v65
	v_add_f32_e32 v73, v111, v73
	v_add_f32_e32 v79, v110, v73
	v_mov_b32_e32 v110, v87
	v_mov_b32_e32 v111, v96
	v_pk_mul_f32 v[96:97], v[110:111], v[130:131]
	v_mul_f32_e32 v73, 0xbfb8aa3b, v79
	v_mul_f32_e32 v156, v49, v53
	v_add_f32_e32 v53, v97, v40
	v_rcp_f32_e32 v65, v65
	v_exp_f32_e32 v73, v73
	v_add_f32_e32 v53, v96, v53
	v_pk_mul_f32 v[96:97], v[82:83], v[136:137]
	v_mul_f32_e32 v102, v57, v45
	v_add_f32_e32 v53, v97, v53
	v_add_f32_e32 v53, v96, v53
	v_mov_b32_e32 v96, v81
	v_mov_b32_e32 v97, v88
	v_pk_mul_f32 v[88:89], v[96:97], v[32:33]
	v_mul_f32_e32 v49, v59, v65
	v_add_f32_e32 v45, 1.0, v73
	v_add_f32_e32 v59, v89, v41
	v_mov_b32_e32 v73, v80
	v_add_f32_e32 v59, v88, v59
	v_pk_mul_f32 v[88:89], v[72:73], v[36:37]
	v_mul_f32_e32 v57, 0xbfb8aa3b, v53
	v_add_f32_e32 v59, v89, v59
	v_add_f32_e32 v59, v88, v59
	v_mul_f32_e32 v65, 0xbfb8aa3b, v59
	v_exp_f32_e32 v65, v65
	v_mov_b32_e32 v88, v71
	v_mov_b32_e32 v89, v76
	v_pk_mul_f32 v[76:77], v[88:89], v[132:133]
	v_add_f32_e32 v65, 1.0, v65
	v_rcp_f32_e32 v85, v65
	v_add_f32_e32 v65, v77, v26
	v_add_f32_e32 v88, v76, v65
	v_mov_b32_e32 v65, v70
	v_pk_mul_f32 v[76:77], v[64:65], v[134:135]
	v_exp_f32_e32 v57, v57
	v_add_f32_e32 v77, v77, v88
	v_add_f32_e32 v88, v76, v77
	v_mul_f32_e32 v76, 0xbfb8aa3b, v88
	v_rcp_f32_e32 v45, v45
	v_exp_f32_e32 v76, v76
	v_add_f32_e32 v57, 1.0, v57
	v_rcp_f32_e32 v57, v57
	v_mul_f32_e32 v157, v79, v45
	v_add_f32_e32 v45, 1.0, v76
	v_mov_b32_e32 v76, v61
	v_mov_b32_e32 v77, v66
	v_pk_mul_f32 v[76:77], v[76:77], v[18:19]
	v_mul_f32_e32 v158, v53, v57
	v_mul_f32_e32 v159, v59, v85
	v_add_f32_e32 v53, v77, v27
	v_mov_b32_e32 v59, v60
	v_add_f32_e32 v53, v76, v53
	v_pk_mul_f32 v[76:77], v[58:59], v[22:23]
	v_lshlrev_b32_e32 v110, 2, v148
	v_add_f32_e32 v53, v77, v53
	v_add_f32_e32 v66, v76, v53
	v_mov_b32_e32 v76, v55
	v_mov_b32_e32 v77, v56
	v_mul_f32_e32 v53, 0xbfb8aa3b, v66
	v_pk_mul_f32 v[56:57], v[76:77], v[140:141]
	v_exp_f32_e32 v79, v53
	v_add_f32_e32 v53, v57, v28
	v_add_f32_e32 v76, v56, v53
	v_mov_b32_e32 v53, v54
	v_pk_mul_f32 v[56:57], v[52:53], v[142:143]
	v_rcp_f32_e32 v77, v45
	v_add_f32_e32 v57, v57, v76
	v_add_f32_e32 v76, v56, v57
	v_mul_f32_e32 v56, 0xbfb8aa3b, v76
	v_exp_f32_e32 v56, v56
	v_add_f32_e32 v45, 1.0, v79
	v_rcp_f32_e32 v79, v45
	v_mov_b32_e32 v57, v48
	v_add_f32_e32 v45, 1.0, v56
	v_mov_b32_e32 v56, v51
	v_pk_mul_f32 v[56:57], v[56:57], v[20:21]
	v_rcp_f32_e32 v85, v45
	v_add_f32_e32 v45, v57, v29
	v_add_f32_e32 v48, v56, v45
	v_mov_b32_e32 v45, v50
	v_pk_mul_f32 v[56:57], v[44:45], v[24:25]
	v_mul_f32_e32 v161, v76, v85
	v_add_f32_e32 v48, v57, v48
	v_add_f32_e32 v48, v56, v48
	v_mul_f32_e32 v56, 0xbfb8aa3b, v48
	v_exp_f32_e32 v56, v56
	v_mul_f32_e32 v160, v88, v77
	v_mul_f32_e32 v66, v66, v79
	v_pk_mul_f32 v[54:55], v[54:55], v[140:141]
	v_add_f32_e32 v76, 1.0, v56
	v_pk_mul_f32 v[56:57], v[68:69], v[128:129]
	v_rcp_f32_e32 v76, v76
	v_add_f32_e32 v57, v57, v38
	v_add_f32_e32 v68, v56, v57
	v_pk_mul_f32 v[56:57], v[118:119], v[138:139]
	v_mul_f32_e32 v48, v48, v76
	v_add_f32_e32 v57, v57, v68
	v_add_f32_e32 v68, v56, v57
	v_mul_f32_e32 v56, 0xbfb8aa3b, v68
	v_exp_f32_e32 v69, v56
	v_pk_mul_f32 v[56:57], v[94:95], v[30:31]
	v_add_f32_e32 v55, v55, v28
	v_add_f32_e32 v57, v57, v39
	v_add_f32_e32 v77, v56, v57
	v_pk_mul_f32 v[56:57], v[112:113], v[34:35]
	v_pk_mul_f32 v[50:51], v[50:51], v[20:21]
	v_add_f32_e32 v57, v57, v77
	v_add_f32_e32 v77, v56, v57
	v_mul_f32_e32 v56, 0xbfb8aa3b, v77
	v_exp_f32_e32 v56, v56
	v_add_f32_e32 v57, 1.0, v69
	v_rcp_f32_e32 v69, v57
	v_add_f32_e32 v51, v51, v29
	v_add_f32_e32 v56, 1.0, v56
	v_rcp_f32_e32 v79, v56
	v_pk_mul_f32 v[56:57], v[86:87], v[130:131]
	v_mul_f32_e32 v68, v68, v69
	v_add_f32_e32 v57, v57, v40
	v_add_f32_e32 v85, v56, v57
	v_pk_mul_f32 v[56:57], v[106:107], v[136:137]
	v_mul_f32_e32 v69, v77, v79
	v_add_f32_e32 v57, v57, v85
	v_add_f32_e32 v85, v56, v57
	v_mul_f32_e32 v56, 0xbfb8aa3b, v85
	v_exp_f32_e32 v56, v56
	v_pk_mul_f32 v[30:31], v[90:91], v[30:31]
	v_bfe_u32 v112, v146, 6, 1
	v_add_f32_e32 v31, v31, v39
	v_add_f32_e32 v76, 1.0, v56
	v_pk_mul_f32 v[56:57], v[80:81], v[32:33]
	v_add_f32_e32 v39, v30, v31
	v_add_f32_e32 v57, v57, v41
	v_add_f32_e32 v77, v56, v57
	v_pk_mul_f32 v[56:57], v[100:101], v[36:37]
	v_pk_mul_f32 v[30:31], v[126:127], v[34:35]
	v_add_f32_e32 v57, v57, v77
	v_add_f32_e32 v77, v56, v57
	v_mul_f32_e32 v56, 0xbfb8aa3b, v77
	v_exp_f32_e32 v79, v56
	v_pk_mul_f32 v[56:57], v[70:71], v[132:133]
	v_rcp_f32_e32 v71, v76
	v_add_f32_e32 v57, v57, v26
	v_add_f32_e32 v70, v56, v57
	v_pk_mul_f32 v[56:57], v[98:99], v[134:135]
	v_add_f32_e32 v31, v31, v39
	v_add_f32_e32 v57, v57, v70
	v_add_f32_e32 v70, v56, v57
	v_mul_f32_e32 v56, 0xbfb8aa3b, v70
	v_exp_f32_e32 v56, v56
	v_add_f32_e32 v57, 1.0, v79
	v_rcp_f32_e32 v76, v57
	v_add_f32_e32 v34, v30, v31
	v_add_f32_e32 v56, 1.0, v56
	v_rcp_f32_e32 v79, v56
	v_pk_mul_f32 v[56:57], v[60:61], v[18:19]
	v_mul_f32_e32 v30, 0xbfb8aa3b, v34
	v_add_f32_e32 v57, v57, v27
	v_add_f32_e32 v60, v56, v57
	v_pk_mul_f32 v[56:57], v[92:93], v[22:23]
	v_mul_f32_e32 v70, v70, v79
	v_add_f32_e32 v57, v57, v60
	v_mul_f32_e32 v60, v85, v71
	v_mov_b32_e32 v85, v52
	v_add_f32_e32 v71, v54, v55
	v_pk_mul_f32 v[54:55], v[84:85], v[142:143]
	v_mov_b32_e32 v79, v44
	v_add_f32_e32 v55, v55, v71
	v_add_f32_e32 v71, v50, v51
	v_pk_mul_f32 v[50:51], v[78:79], v[24:25]
	v_add_f32_e32 v54, v54, v55
	v_add_f32_e32 v51, v51, v71
	v_add_f32_e32 v71, v50, v51
	v_mul_f32_e32 v55, 0xbfb8aa3b, v54
	v_mul_f32_e32 v50, 0xbfb8aa3b, v71
	v_exp_f32_e32 v55, v55
	v_exp_f32_e32 v50, v50
	v_mul_f32_e32 v61, v77, v76
	v_exp_f32_e32 v35, v30
	v_add_f32_e32 v51, 1.0, v55
	v_add_f32_e32 v50, 1.0, v50
	v_rcp_f32_e32 v55, v51
	v_rcp_f32_e32 v76, v50
	v_pk_mul_f32 v[50:51], v[62:63], v[128:129]
	v_pk_mul_f32 v[30:31], v[82:83], v[130:131]
	v_add_f32_e32 v38, v51, v38
	v_add_f32_e32 v31, v31, v40
	v_add_f32_e32 v38, v50, v38
	v_pk_mul_f32 v[50:51], v[116:117], v[138:139]
	v_add_f32_e32 v39, v30, v31
	v_pk_mul_f32 v[30:31], v[124:125], v[136:137]
	v_add_f32_e32 v38, v51, v38
	v_add_f32_e32 v31, v31, v39
	v_add_f32_e32 v38, v50, v38
	v_add_f32_e32 v39, v30, v31
	v_mul_f32_e32 v50, 0xbfb8aa3b, v38
	v_mul_f32_e32 v30, 0xbfb8aa3b, v39
	v_exp_f32_e32 v50, v50
	v_exp_f32_e32 v30, v30
	v_add_f32_e32 v31, 1.0, v35
	v_rcp_f32_e32 v35, v31
	v_add_f32_e32 v50, 1.0, v50
	v_add_f32_e32 v30, 1.0, v30
	v_rcp_f32_e32 v40, v50
	v_rcp_f32_e32 v50, v30
	v_pk_mul_f32 v[30:31], v[72:73], v[32:33]
	v_mul_f32_e32 v63, v71, v76
	v_add_f32_e32 v31, v31, v41
	v_add_f32_e32 v32, v30, v31
	v_pk_mul_f32 v[30:31], v[122:123], v[36:37]
	v_mul_f32_e32 v71, v34, v35
	v_add_f32_e32 v31, v31, v32
	v_add_f32_e32 v32, v30, v31
	v_mul_f32_e32 v30, 0xbfb8aa3b, v32
	v_exp_f32_e32 v30, v30
	v_pk_mul_f32 v[18:19], v[58:59], v[18:19]
	v_add_f32_e32 v56, v56, v57
	v_add_f32_e32 v19, v19, v27
	v_add_f32_e32 v30, 1.0, v30
	v_rcp_f32_e32 v34, v30
	v_pk_mul_f32 v[30:31], v[64:65], v[132:133]
	v_add_f32_e32 v27, v18, v19
	v_add_f32_e32 v26, v31, v26
	v_add_f32_e32 v26, v30, v26
	v_pk_mul_f32 v[30:31], v[120:121], v[134:135]
	v_pk_mul_f32 v[18:19], v[114:115], v[22:23]
	v_add_f32_e32 v26, v31, v26
	v_add_f32_e32 v26, v30, v26
	v_add_f32_e32 v19, v19, v27
	v_mul_f32_e32 v30, 0xbfb8aa3b, v26
	v_add_f32_e32 v27, v18, v19
	v_exp_f32_e32 v30, v30
	v_mul_f32_e32 v18, 0xbfb8aa3b, v27
	v_exp_f32_e32 v18, v18
	v_mul_f32_e32 v31, v32, v34
	v_add_f32_e32 v19, 1.0, v30
	v_rcp_f32_e32 v30, v19
	v_add_f32_e32 v32, 1.0, v18
	v_pk_mul_f32 v[18:19], v[52:53], v[140:141]
	v_mul_f32_e32 v57, 0xbfb8aa3b, v56
	v_add_f32_e32 v19, v19, v28
	v_add_f32_e32 v22, v18, v19
	v_pk_mul_f32 v[18:19], v[108:109], v[142:143]
	v_exp_f32_e32 v57, v57
	v_add_f32_e32 v19, v19, v22
	v_add_f32_e32 v28, v18, v19
	v_mul_f32_e32 v18, 0xbfb8aa3b, v28
	v_exp_f32_e32 v52, v18
	v_pk_mul_f32 v[18:19], v[44:45], v[20:21]
	v_lshlrev_b64 v[92:93], 2, v[42:43]
	v_add_f32_e32 v19, v19, v29
	v_add_f32_e32 v20, v18, v19
	v_pk_mul_f32 v[18:19], v[104:105], v[24:25]
	v_add_f32_e32 v57, 1.0, v57
	v_add_f32_e32 v19, v19, v20
	v_add_f32_e32 v29, v18, v19
	v_lshl_add_u64 v[18:19], s[20:21], 0, v[92:93]
	s_lshl_b64 s[20:21], s[16:17], 9
	s_add_u32 s20, s26, s20
	s_addc_u32 s21, s27, s21
	s_lshl_b32 s16, s4, 10
	v_rcp_f32_e32 v57, v57
	v_and_or_b32 v80, v151, s34, v147
	s_add_u32 s22, s24, s16
	v_lshl_add_u64 v[18:19], v[18:19], 0, v[74:75]
	s_addc_u32 s23, s25, 0
	v_ashrrev_i32_e32 v81, 31, v80
	v_lshlrev_b32_e32 v111, 5, v112
	v_lshl_add_u64 v[20:21], v[18:19], 0, s[14:15]
	v_add_co_u32_e32 v18, vcc, s35, v18
	s_add_u32 s42, s60, s16
	v_lshl_add_u64 v[82:83], s[18:19], 0, v[80:81]
	v_or_b32_e32 v58, v111, v110
	v_addc_co_u32_e32 v19, vcc, 0, v19, vcc
	s_addc_u32 s43, s61, 0
	v_lshlrev_b64 v[88:89], 11, v[82:83]
	v_or_b32_e32 v78, 16, v80
	v_mul_f32_e32 v51, v56, v57
	v_mul_f32_e32 v62, v54, v55
	v_mul_f32_e32 v33, v38, v40
	v_mul_f32_e32 v50, v39, v50
	global_load_dwordx4 v[38:41], v[18:19], off
	global_load_dwordx4 v[34:37], v[20:21], off offset:48
	global_load_dwordx4 v[42:45], v[20:21], off offset:32
	global_load_dwordx4 v[54:57], v[20:21], off offset:16
	v_lshlrev_b64 v[86:87], 2, v[80:81]
	v_lshl_add_u64 v[20:21], s[22:23], 0, v[88:89]
	v_mov_b64_e32 v[22:23], s[42:43]
	v_lshlrev_b32_e32 v76, 1, v58
	v_mov_b32_e32 v77, v75
	v_ashrrev_i32_e32 v79, 31, v78
	v_lshl_add_u64 v[18:19], s[20:21], 0, v[86:87]
	v_mul_lo_u32 v81, v83, s28
	v_mad_u64_u32 v[24:25], s[20:21], v82, s28, v[22:23]
	v_lshl_add_u64 v[20:21], v[20:21], 0, v[76:77]
	v_lshl_add_u64 v[84:85], s[18:19], 0, v[78:79]
	v_add_u32_e32 v25, v81, v25
	global_load_dword v83, v[18:19], off
	global_load_dwordx2 v[94:95], v[20:21], off
	global_load_dwordx2 v[98:99], v[20:21], off offset:32
	global_load_dword v113, v[18:19], off offset:64
	v_lshlrev_b64 v[90:91], 11, v[84:85]
	v_mul_lo_u32 v79, v85, s28
	v_mad_u64_u32 v[20:21], s[18:19], v84, s28, v[22:23]
	v_lshl_add_u64 v[24:25], v[24:25], 0, v[76:77]
	v_lshl_add_u64 v[18:19], s[22:23], 0, v[90:91]
	v_add_u32_e32 v21, v79, v21
	v_lshl_add_u64 v[18:19], v[18:19], 0, v[76:77]
	v_lshl_add_u64 v[20:21], v[20:21], 0, v[76:77]
	global_load_dwordx2 v[106:107], v[24:25], off
	global_load_dwordx2 v[126:127], v[24:25], off offset:32
	global_load_dwordx2 v[104:105], v[18:19], off
	global_load_dwordx2 v[96:97], v[18:19], off offset:32
	global_load_dwordx2 v[108:109], v[20:21], off
	global_load_dwordx2 v[100:101], v[20:21], off offset:32
	v_mul_f32_e32 v53, 0xbfb8aa3b, v29
	v_exp_f32_e32 v18, v53
	v_add_f32_e32 v20, 1.0, v52
	v_rcp_f32_e32 v19, v32
	v_rcp_f32_e32 v20, v20
	v_add_f32_e32 v18, 1.0, v18
	v_rcp_f32_e32 v18, v18
	v_mul_f32_e32 v23, v26, v30
	v_lshl_add_u32 v22, v152, 1, 0
	v_mul_f32_e32 v26, v27, v19
	v_mul_f32_e32 v27, v28, v20
	v_cvt_pk_bf16_f32 v20, v154, v155
	v_mad_u64_u32 v[24:25], s[18:19], v46, s33, v[22:23]
	v_mul_f32_e32 v28, v29, v18
	v_cvt_pk_bf16_f32 v18, v47, v67
	v_cvt_pk_bf16_f32 v19, v103, v153
	v_cvt_pk_bf16_f32 v21, v102, v156
	ds_write_b128 v24, v[18:21]
	v_cvt_pk_bf16_f32 v20, v160, v66
	v_cvt_pk_bf16_f32 v18, v49, v157
	v_cvt_pk_bf16_f32 v19, v158, v159
	v_cvt_pk_bf16_f32 v21, v161, v48
	ds_write_b128 v24, v[18:21] offset:272
	v_cvt_pk_bf16_f32 v20, v70, v51
	v_cvt_pk_bf16_f32 v18, v68, v69
	v_cvt_pk_bf16_f32 v19, v60, v61
	v_cvt_pk_bf16_f32 v21, v62, v63
	ds_write_b128 v24, v[18:21] offset:544
	v_cvt_pk_bf16_f32 v20, v23, v26
	v_or_b32_e32 v23, 3, v151
	v_cvt_pk_bf16_f32 v18, v33, v71
	v_mad_u64_u32 v[22:23], s[18:19], v23, s33, v[22:23]
	v_cvt_pk_bf16_f32 v19, v50, v31
	v_cvt_pk_bf16_f32 v21, v27, v28
	ds_write_b128 v22, v[18:21]
	v_mul_lo_u32 v18, v150, s33
	v_lshl_add_u32 v46, v148, 4, 0
	v_or_b32_e32 v47, v111, v147
	v_add3_u32 v128, 0, v18, v2
	v_mad_u64_u32 v[22:23], s[18:19], v78, s33, v[46:47]
	v_mad_u64_u32 v[30:31], s[18:19], v80, s33, v[46:47]
	v_mad_u32_u24 v129, v47, s33, v46
	ds_write_b128 v128, v[14:17] offset:34816
	ds_write_b128 v128, v[6:9] offset:34832
	s_waitcnt lgkmcnt(0)
	s_barrier
	s_add_i32 m0, s98, 0x0
	s_nop 0
	global_load_lds_dwordx4 v239, s[96:97]
	s_add_i32 m0, s98, 0x3f0
	s_nop 0
	global_load_lds_dwordx4 v239, s[96:97] offset:16
	s_add_i32 m0, s98, 0x7e0
	s_nop 0
	global_load_lds_dwordx4 v239, s[96:97] offset:32
	s_add_i32 m0, s98, 0xbd0
	s_nop 0
	global_load_lds_dwordx4 v239, s[96:97] offset:48
	s_add_u32 s96, s96, 0x8000
	s_addc_u32 s97, s97, 0
	ds_read_b128 v[2:5], v22 offset:192
	ds_read_b128 v[10:13], v22 offset:128
	ds_read_b128 v[6:9], v30 offset:192
	ds_read_b128 v[14:17], v30 offset:128
	ds_read_b128 v[18:21], v22 offset:64
	ds_read_b128 v[26:29], v22
	ds_read_b128 v[22:25], v30 offset:64
	ds_read_b128 v[30:33], v30
	ds_read_b128 v[46:49], v129 offset:34816
	ds_read_b128 v[50:53], v129 offset:34880
	ds_read_b128 v[58:61], v129 offset:39168
	ds_read_b128 v[62:65], v129 offset:39232
	ds_read_b128 v[66:69], v129 offset:34944
	ds_read_b128 v[70:73], v129 offset:35008
	ds_read_b128 v[114:117], v129 offset:39296
	ds_read_b128 v[118:121], v129 offset:39360
	s_waitcnt vmcnt(9)
	v_lshlrev_b32_e32 v85, 16, v106
	s_waitcnt lgkmcnt(7)
	v_mfma_f32_16x16x32_bf16 v[122:125], v[46:49], v[30:33], 0
	v_mul_f32_e32 v102, 0xbfb8aa3b, v85
	v_exp_f32_e32 v102, v102
	v_and_b32_e32 v106, 0xffff0000, v106
	s_waitcnt lgkmcnt(6)
	v_mfma_f32_16x16x32_bf16 v[122:125], v[50:53], v[22:25], v[122:125]
	v_mul_f32_e32 v130, 0xbfb8aa3b, v106
	v_add_f32_e32 v102, 1.0, v102
	v_rcp_f32_e32 v102, v102
	v_exp_f32_e32 v134, v130
	s_waitcnt lgkmcnt(3)
	v_mfma_f32_16x16x32_bf16 v[122:125], v[66:69], v[14:17], v[122:125]
	v_mul_f32_e32 v83, 0x3fb8aa3b, v83
	v_mul_f32_e32 v85, v102, v85
	v_add_f32_e32 v102, 1.0, v134
	v_exp_f32_e32 v83, v83
	s_waitcnt lgkmcnt(2)
	v_mfma_f32_16x16x32_bf16 v[122:125], v[70:73], v[6:9], v[122:125]
	v_rcp_f32_e32 v102, v102
	v_lshlrev_b32_e32 v103, 16, v94
	v_and_b32_e32 v94, 0xffff0000, v94
	v_mfma_f32_16x16x32_bf16 v[46:49], v[46:49], v[26:29], 0
	v_mul_f32_e32 v102, v102, v106
	s_nop 2
	v_fmac_f32_e32 v94, v83, v123
	v_fmac_f32_e32 v103, v83, v122
	v_mul_f32_e32 v94, v102, v94
	v_lshlrev_b32_e32 v102, 16, v107
	v_mul_f32_e32 v85, v85, v103
	v_mul_f32_e32 v103, 0xbfb8aa3b, v102
	v_mfma_f32_16x16x32_bf16 v[46:49], v[50:53], v[18:21], v[46:49]
	v_exp_f32_e32 v103, v103
	v_lshlrev_b32_e32 v106, 16, v95
	v_fmac_f32_e32 v106, v83, v124
	v_mfma_f32_16x16x32_bf16 v[130:133], v[58:61], v[30:33], 0
	v_add_f32_e32 v103, 1.0, v103
	v_rcp_f32_e32 v103, v103
	v_and_b32_e32 v107, 0xffff0000, v107
	v_mfma_f32_16x16x32_bf16 v[58:61], v[58:61], v[26:29], 0
	v_mul_f32_e32 v122, 0xbfb8aa3b, v107
	s_or_b32 s20, s40, 1
	s_or_b32 s16, s39, s20
	v_mfma_f32_16x16x32_bf16 v[46:49], v[66:69], v[10:13], v[46:49]
	s_lshl_b64 s[18:19], s[16:17], 15
	s_add_u32 s18, s74, s18
	s_addc_u32 s19, s75, s19
	v_mfma_f32_16x16x32_bf16 v[130:133], v[62:65], v[22:25], v[130:133]
	v_cvt_pk_bf16_f32 v38, v38, v39
	v_cvt_pk_bf16_f32 v39, v40, v41
	v_cvt_pk_bf16_f32 v40, v54, v55
	v_mfma_f32_16x16x32_bf16 v[50:53], v[62:65], v[18:21], v[58:61]
	v_exp_f32_e32 v62, v122
	v_and_b32_e32 v64, 0xffff0000, v95
	v_fmac_f32_e32 v64, v83, v125
	v_mfma_f32_16x16x32_bf16 v[70:73], v[70:73], v[2:5], v[46:49]
	v_mul_f32_e32 v58, v103, v102
	v_mul_f32_e32 v63, v58, v106
	v_add_f32_e32 v62, 1.0, v62
	s_waitcnt vmcnt(8)
	v_lshlrev_b32_e32 v46, 16, v126
	v_mul_f32_e32 v47, 0xbfb8aa3b, v46
	v_exp_f32_e32 v47, v47
	s_waitcnt lgkmcnt(1)
	v_mfma_f32_16x16x32_bf16 v[58:61], v[114:117], v[14:17], v[130:133]
	v_and_b32_e32 v49, 0xffff0000, v126
	v_lshlrev_b32_e32 v48, 16, v98
	v_add_f32_e32 v47, 1.0, v47
	v_mfma_f32_16x16x32_bf16 v[50:53], v[114:117], v[10:13], v[50:53]
	v_rcp_f32_e32 v47, v47
	v_rcp_f32_e32 v62, v62
	v_cvt_pk_bf16_f32 v116, v85, v94
	s_waitcnt lgkmcnt(0)
	v_mfma_f32_16x16x32_bf16 v[58:61], v[118:121], v[6:9], v[58:61]
	v_mul_f32_e32 v46, v47, v46
	v_and_b32_e32 v47, 0xffff0000, v98
	v_mul_f32_e32 v62, v62, v107
	v_mfma_f32_16x16x32_bf16 v[66:69], v[118:121], v[2:5], v[50:53]
	v_mul_f32_e32 v62, v62, v64
	s_nop 2
	v_fmac_f32_e32 v48, v83, v58
	v_mul_f32_e32 v46, v46, v48
	v_mul_f32_e32 v50, 0xbfb8aa3b, v49
	v_exp_f32_e32 v50, v50
	v_fmac_f32_e32 v47, v83, v59
	v_lshlrev_b32_e32 v52, 16, v99
	v_fmac_f32_e32 v52, v83, v60
	v_add_f32_e32 v48, 1.0, v50
	v_lshlrev_b32_e32 v50, 16, v127
	v_rcp_f32_e32 v48, v48
	v_mul_f32_e32 v51, 0xbfb8aa3b, v50
	v_exp_f32_e32 v51, v51
	v_mul_f32_e32 v64, v94, v94
	v_mul_f32_e32 v48, v48, v49
	v_and_b32_e32 v49, 0xffff0000, v127
	v_mul_f32_e32 v47, v48, v47
	v_add_f32_e32 v48, 1.0, v51
	v_mul_f32_e32 v51, 0xbfb8aa3b, v49
	v_rcp_f32_e32 v48, v48
	v_exp_f32_e32 v51, v51
	v_cvt_pk_bf16_f32 v117, v46, v47
	v_fmac_f32_e32 v64, v85, v85
	v_mul_f32_e32 v48, v48, v50
	v_add_f32_e32 v50, 1.0, v51
	v_rcp_f32_e32 v50, v50
	v_and_b32_e32 v51, 0xffff0000, v99
	v_mul_f32_e32 v48, v48, v52
	v_fmac_f32_e32 v51, v83, v61
	v_mul_f32_e32 v49, v50, v49
	v_mul_f32_e32 v50, v47, v47
	v_fmac_f32_e32 v50, v46, v46
	v_mul_f32_e32 v46, 0x3fb8aa3b, v113
	v_exp_f32_e32 v113, v46
	s_waitcnt vmcnt(5)
	v_lshlrev_b32_e32 v46, 16, v108
	v_mul_f32_e32 v47, 0xbfb8aa3b, v46
	v_exp_f32_e32 v47, v47
	v_mul_f32_e32 v49, v49, v51
	v_fmac_f32_e32 v50, v48, v48
	v_cvt_pk_bf16_f32 v118, v48, v49
	v_lshlrev_b32_e32 v48, 16, v104
	v_fmac_f32_e32 v48, v113, v70
	v_add_f32_e32 v47, 1.0, v47
	v_and_b32_e32 v70, 0xffff0000, v108
	v_fmac_f32_e32 v50, v49, v49
	v_rcp_f32_e32 v47, v47
	v_mul_f32_e32 v49, 0xbfb8aa3b, v70
	v_exp_f32_e32 v49, v49
	v_and_b32_e32 v83, 0xffff0000, v104
	v_mul_f32_e32 v46, v47, v46
	v_mul_f32_e32 v119, v46, v48
	v_add_f32_e32 v46, 1.0, v49
	v_lshlrev_b32_e32 v104, 16, v109
	v_rcp_f32_e32 v85, v46
	v_mul_f32_e32 v46, 0xbfb8aa3b, v104
	v_exp_f32_e32 v108, v46
	v_lshl_add_u64 v[46:47], s[18:19], 0, v[92:93]
	s_lshl_b64 s[18:19], s[16:17], 9
	s_add_u32 s18, s26, s18
	s_addc_u32 s19, s27, s19
	s_lshl_b32 s16, s20, 7
	s_add_u32 s20, s24, s16
	s_addc_u32 s21, s25, 0
	v_fmac_f32_e32 v64, v63, v63
	v_lshl_add_u64 v[46:47], v[46:47], 0, v[74:75]
	s_add_u32 s22, s60, s16
	v_fmac_f32_e32 v64, v62, v62
	v_cvt_pk_bf16_f32 v115, v63, v62
	v_lshl_add_u64 v[62:63], v[46:47], 0, s[14:15]
	v_add_co_u32_e32 v46, vcc, s35, v46
	s_addc_u32 s23, s61, 0
	v_lshl_add_u64 v[98:99], s[20:21], 0, v[88:89]
	v_addc_co_u32_e32 v47, vcc, 0, v47, vcc
	v_lshl_add_u64 v[94:95], s[18:19], 0, v[86:87]
	v_mov_b64_e32 v[102:103], s[22:23]
	v_lshl_add_u64 v[98:99], v[98:99], 0, v[76:77]
	v_add_f32_e32 v137, v64, v50
	s_waitcnt vmcnt(0)
	ds_read_b128 v[50:53], v240 offset:0
	s_nop 0
	ds_read_b128 v[46:49], v240 offset:3072
	ds_read_b128 v[58:61], v240 offset:2048
	s_nop 0
	ds_read_b128 v[62:65], v240 offset:1024
	v_mad_u64_u32 v[106:107], s[18:19], v82, s28, v[102:103]
	global_load_dword v124, v[94:95], off
	global_load_dwordx2 v[142:143], v[98:99], off
	global_load_dwordx2 v[154:155], v[98:99], off offset:32
	global_load_dword v149, v[94:95], off offset:64
	v_mad_u64_u32 v[98:99], s[18:19], v84, s28, v[102:103]
	v_add_u32_e32 v107, v81, v107
	v_lshl_add_u64 v[94:95], s[20:21], 0, v[90:91]
	v_add_u32_e32 v99, v79, v99
	v_lshl_add_u64 v[106:107], v[106:107], 0, v[76:77]
	v_lshl_add_u64 v[94:95], v[94:95], 0, v[76:77]
	v_lshl_add_u64 v[98:99], v[98:99], 0, v[76:77]
	global_load_dwordx2 v[156:157], v[106:107], off
	global_load_dwordx2 v[158:159], v[106:107], off offset:32
	global_load_dwordx2 v[102:103], v[94:95], off
	s_nop 0
	global_load_dwordx2 v[94:95], v[94:95], off offset:32
	s_nop 0
	global_load_dwordx2 v[106:107], v[98:99], off
	s_nop 0
	global_load_dwordx2 v[98:99], v[98:99], off offset:32
	v_fmac_f32_e32 v83, v113, v71
	v_mul_f32_e32 v70, v85, v70
	v_and_b32_e32 v71, 0xffff0000, v109
	v_mul_f32_e32 v130, v70, v83
	v_mul_f32_e32 v83, 0xbfb8aa3b, v71
	v_exp_f32_e32 v83, v83
	v_add_f32_e32 v70, 1.0, v108
	v_rcp_f32_e32 v70, v70
	v_lshlrev_b32_e32 v85, 16, v105
	v_fmac_f32_e32 v85, v113, v72
	v_add_f32_e32 v72, 1.0, v83
	v_rcp_f32_e32 v72, v72
	v_mul_f32_e32 v70, v70, v104
	v_mul_f32_e32 v131, v70, v85
	v_and_b32_e32 v70, 0xffff0000, v105
	v_fmac_f32_e32 v70, v113, v73
	v_mul_f32_e32 v71, v72, v71
	v_mul_f32_e32 v132, v71, v70
	s_waitcnt vmcnt(14)
	v_lshlrev_b32_e32 v70, 16, v100
	v_mul_f32_e32 v71, 0xbfb8aa3b, v70
	v_exp_f32_e32 v71, v71
	v_and_b32_e32 v73, 0xffff0000, v100
	v_mul_f32_e32 v100, 0xbfb8aa3b, v73
	v_exp_f32_e32 v100, v100
	v_add_f32_e32 v71, 1.0, v71
	v_rcp_f32_e32 v71, v71
	v_lshlrev_b32_e32 v72, 16, v96
	v_fmac_f32_e32 v72, v113, v66
	v_cvt_pk_bf16_f32 v41, v56, v57
	v_mul_f32_e32 v66, v71, v70
	v_mul_f32_e32 v133, v66, v72
	v_add_f32_e32 v66, 1.0, v100
	v_lshlrev_b32_e32 v70, 16, v101
	v_rcp_f32_e32 v66, v66
	v_mul_f32_e32 v71, 0xbfb8aa3b, v70
	v_exp_f32_e32 v71, v71
	v_and_b32_e32 v72, 0xffff0000, v96
	v_fmac_f32_e32 v72, v113, v67
	v_mul_f32_e32 v66, v66, v73
	v_add_f32_e32 v67, 1.0, v71
	v_mul_f32_e32 v134, v66, v72
	v_lshlrev_b32_e32 v66, 16, v97
	v_and_b32_e32 v96, 0xffff0000, v101
	v_rcp_f32_e32 v67, v67
	v_fmac_f32_e32 v66, v113, v68
	v_mul_f32_e32 v68, 0xbfb8aa3b, v96
	v_exp_f32_e32 v68, v68
	v_mul_f32_e32 v67, v67, v70
	v_mul_f32_e32 v135, v67, v66
	v_and_b32_e32 v97, 0xffff0000, v97
	v_add_f32_e32 v66, 1.0, v68
	v_cvt_pk_bf16_f32 v42, v42, v43
	v_cvt_pk_bf16_f32 v43, v44, v45
	v_cvt_pk_bf16_f32 v44, v34, v35
	v_cvt_pk_bf16_f32 v45, v36, v37
	v_fmac_f32_e32 v97, v113, v69
	v_rcp_f32_e32 v100, v66
	ds_write_b128 v128, v[38:41] offset:52224
	ds_write_b128 v128, v[42:45] offset:52240
	s_waitcnt lgkmcnt(0)
	s_barrier
	s_add_i32 m0, s98, 0x0
	s_nop 0
	global_load_lds_dwordx4 v239, s[96:97]
	s_add_i32 m0, s98, 0x3f0
	s_nop 0
	global_load_lds_dwordx4 v239, s[96:97] offset:16
	s_add_i32 m0, s98, 0x7e0
	s_nop 0
	global_load_lds_dwordx4 v239, s[96:97] offset:32
	s_add_i32 m0, s98, 0xbd0
	s_nop 0
	global_load_lds_dwordx4 v239, s[96:97] offset:48
	s_add_u32 s96, s96, 0x8000
	s_addc_u32 s97, s97, 0
	ds_read_b128 v[34:37], v129 offset:52224
	ds_read_b128 v[38:41], v129 offset:52288
	ds_read_b128 v[42:45], v129 offset:56576
	ds_read_b128 v[54:57], v129 offset:56640
	ds_read_b128 v[66:69], v129 offset:52352
	ds_read_b128 v[70:73], v129 offset:52416
	ds_read_b128 v[120:123], v129 offset:56704
	ds_read_b128 v[138:141], v129 offset:56768
	v_mul_f32_e32 v96, v100, v96
	v_mul_f32_e32 v136, v96, v97
	v_cvt_pk_bf16_f32 v85, v119, v130
	v_cvt_pk_bf16_f32 v83, v131, v132
	v_cvt_pk_bf16_f32 v114, v133, v134
	v_cvt_pk_bf16_f32 v113, v135, v136
	s_waitcnt vmcnt(13)
	v_mul_f32_e32 v96, 0x3fb8aa3b, v124
	s_waitcnt lgkmcnt(7)
	v_mfma_f32_16x16x32_bf16 v[124:127], v[34:37], v[30:33], 0
	s_waitcnt vmcnt(9)
	v_lshlrev_b32_e32 v97, 16, v156
	v_mul_f32_e32 v100, 0xbfb8aa3b, v97
	v_exp_f32_e32 v100, v100
	s_waitcnt lgkmcnt(6)
	v_mfma_f32_16x16x32_bf16 v[124:127], v[38:41], v[22:25], v[124:127]
	v_and_b32_e32 v104, 0xffff0000, v156
	v_mul_f32_e32 v105, 0xbfb8aa3b, v104
	v_add_f32_e32 v100, 1.0, v100
	s_waitcnt lgkmcnt(3)
	v_mfma_f32_16x16x32_bf16 v[124:127], v[66:69], v[14:17], v[124:127]
	v_rcp_f32_e32 v100, v100
	v_exp_f32_e32 v105, v105
	v_exp_f32_e32 v96, v96
	s_waitcnt lgkmcnt(2)
	v_mfma_f32_16x16x32_bf16 v[124:127], v[70:73], v[6:9], v[124:127]
	v_mul_f32_e32 v97, v100, v97
	v_add_f32_e32 v100, 1.0, v105
	v_rcp_f32_e32 v100, v100
	v_lshlrev_b32_e32 v101, 16, v142
	v_mfma_f32_16x16x32_bf16 v[34:37], v[34:37], v[26:29], 0
	s_nop 2
	v_fmac_f32_e32 v101, v96, v124
	v_mul_f32_e32 v97, v97, v101
	v_and_b32_e32 v101, 0xffff0000, v142
	v_fmac_f32_e32 v101, v96, v125
	v_mul_f32_e32 v100, v100, v104
	v_mul_f32_e32 v100, v100, v101
	v_lshlrev_b32_e32 v101, 16, v157
	v_mul_f32_e32 v104, 0xbfb8aa3b, v101
	v_exp_f32_e32 v104, v104
	v_mfma_f32_16x16x32_bf16 v[150:153], v[42:45], v[30:33], 0
	v_lshlrev_b32_e32 v105, 16, v143
	v_fmac_f32_e32 v105, v96, v126
	v_add_f32_e32 v104, 1.0, v104
	v_mfma_f32_16x16x32_bf16 v[34:37], v[38:41], v[18:21], v[34:37]
	v_rcp_f32_e32 v104, v104
	v_and_b32_e32 v108, 0xffff0000, v157
	v_mul_f32_e32 v109, 0xbfb8aa3b, v108
	v_mfma_f32_16x16x32_bf16 v[42:45], v[42:45], v[26:29], 0
	s_or_b32 s20, s40, 2
	s_or_b32 s16, s39, s20
	s_lshl_b64 s[18:19], s[16:17], 15
	v_mfma_f32_16x16x32_bf16 v[150:153], v[54:57], v[22:25], v[150:153]
	s_add_u32 s18, s74, s18
	s_addc_u32 s19, s75, s19
	v_mfma_f32_16x16x32_bf16 v[34:37], v[66:69], v[10:13], v[34:37]
	v_mfma_f32_16x16x32_bf16 v[38:41], v[54:57], v[18:21], v[42:45]
	v_exp_f32_e32 v54, v109
	v_and_b32_e32 v56, 0xffff0000, v143
	v_fmac_f32_e32 v56, v96, v127
	v_mul_f32_e32 v42, v104, v101
	v_mul_f32_e32 v55, v42, v105
	s_waitcnt lgkmcnt(1)
	v_mfma_f32_16x16x32_bf16 v[42:45], v[120:123], v[14:17], v[150:153]
	v_add_f32_e32 v54, 1.0, v54
	v_rcp_f32_e32 v54, v54
	v_cvt_pk_bf16_f32 v127, v97, v100
	v_mfma_f32_16x16x32_bf16 v[70:73], v[70:73], v[2:5], v[34:37]
	v_mul_f32_e32 v54, v54, v108
	v_mul_f32_e32 v54, v54, v56
	s_waitcnt vmcnt(8)
	v_lshlrev_b32_e32 v34, 16, v158
	v_mul_f32_e32 v35, 0xbfb8aa3b, v34
	v_exp_f32_e32 v35, v35
	s_waitcnt lgkmcnt(0)
	v_mfma_f32_16x16x32_bf16 v[42:45], v[138:141], v[6:9], v[42:45]
	v_lshlrev_b32_e32 v36, 16, v154
	v_and_b32_e32 v37, 0xffff0000, v158
	v_add_f32_e32 v35, 1.0, v35
	v_rcp_f32_e32 v35, v35
	v_mul_f32_e32 v56, v100, v100
	s_nop 2
	v_fmac_f32_e32 v36, v96, v42
	v_mul_f32_e32 v42, 0xbfb8aa3b, v37
	v_exp_f32_e32 v42, v42
	v_fmac_f32_e32 v56, v97, v97
	v_mul_f32_e32 v34, v35, v34
	v_fmac_f32_e32 v56, v55, v55
	v_mul_f32_e32 v34, v34, v36
	v_add_f32_e32 v36, 1.0, v42
	v_lshlrev_b32_e32 v42, 16, v159
	v_mfma_f32_16x16x32_bf16 v[38:41], v[120:123], v[10:13], v[38:41]
	v_fmac_f32_e32 v56, v54, v54
	v_cvt_pk_bf16_f32 v122, v55, v54
	v_rcp_f32_e32 v36, v36
	v_mul_f32_e32 v54, 0xbfb8aa3b, v42
	v_exp_f32_e32 v54, v54
	v_and_b32_e32 v35, 0xffff0000, v154
	v_fmac_f32_e32 v35, v96, v43
	v_mul_f32_e32 v36, v36, v37
	v_and_b32_e32 v37, 0xffff0000, v159
	v_mul_f32_e32 v35, v36, v35
	v_add_f32_e32 v36, 1.0, v54
	v_mul_f32_e32 v43, 0xbfb8aa3b, v37
	v_rcp_f32_e32 v36, v36
	v_exp_f32_e32 v43, v43
	v_cvt_pk_bf16_f32 v125, v34, v35
	v_lshlrev_b32_e32 v54, 16, v155
	v_mul_f32_e32 v36, v36, v42
	v_add_f32_e32 v42, 1.0, v43
	v_rcp_f32_e32 v42, v42
	v_fmac_f32_e32 v54, v96, v44
	v_and_b32_e32 v43, 0xffff0000, v155
	v_mul_f32_e32 v36, v36, v54
	v_mul_f32_e32 v37, v42, v37
	v_mul_f32_e32 v42, v35, v35
	v_fmac_f32_e32 v42, v34, v34
	v_mul_f32_e32 v34, 0x3fb8aa3b, v149
	v_exp_f32_e32 v123, v34
	s_waitcnt vmcnt(5)
	v_lshlrev_b32_e32 v34, 16, v106
	v_mul_f32_e32 v35, 0xbfb8aa3b, v34
	v_exp_f32_e32 v35, v35
	v_fmac_f32_e32 v43, v96, v45
	v_mul_f32_e32 v37, v37, v43
	v_fmac_f32_e32 v42, v36, v36
	v_cvt_pk_bf16_f32 v126, v36, v37
	v_lshlrev_b32_e32 v36, 16, v102
	v_fmac_f32_e32 v36, v123, v70
	v_add_f32_e32 v35, 1.0, v35
	v_and_b32_e32 v70, 0xffff0000, v106
	v_fmac_f32_e32 v42, v37, v37
	v_rcp_f32_e32 v35, v35
	v_mul_f32_e32 v37, 0xbfb8aa3b, v70
	v_exp_f32_e32 v37, v37
	v_add_f32_e32 v56, v137, v56
	v_mul_f32_e32 v34, v35, v34
	v_mul_f32_e32 v137, v34, v36
	v_add_f32_e32 v34, 1.0, v37
	v_lshlrev_b32_e32 v120, 16, v107
	v_rcp_f32_e32 v106, v34
	v_mul_f32_e32 v34, 0xbfb8aa3b, v120
	v_exp_f32_e32 v121, v34
	v_lshl_add_u64 v[34:35], s[18:19], 0, v[92:93]
	s_lshl_b64 s[18:19], s[16:17], 9
	s_add_u32 s18, s26, s18
	s_addc_u32 s19, s27, s19
	s_lshl_b32 s16, s20, 7
	s_add_u32 s20, s24, s16
	s_addc_u32 s21, s25, 0
	v_lshl_add_u64 v[34:35], v[34:35], 0, v[74:75]
	s_add_u32 s22, s60, s16
	v_lshl_add_u64 v[66:67], v[34:35], 0, s[14:15]
	v_add_co_u32_e32 v34, vcc, s35, v34
	s_addc_u32 s23, s61, 0
	v_lshl_add_u64 v[100:101], s[20:21], 0, v[88:89]
	v_addc_co_u32_e32 v35, vcc, 0, v35, vcc
	v_lshl_add_u64 v[96:97], s[18:19], 0, v[86:87]
	v_mov_b64_e32 v[104:105], s[22:23]
	v_lshl_add_u64 v[100:101], v[100:101], 0, v[76:77]
	v_add_f32_e32 v150, v56, v42
	s_waitcnt vmcnt(0)
	ds_read_b128 v[42:45], v240 offset:0
	s_nop 0
	ds_read_b128 v[34:37], v240 offset:3072
	ds_read_b128 v[54:57], v240 offset:2048
	s_nop 0
	ds_read_b128 v[66:69], v240 offset:1024
	v_mad_u64_u32 v[108:109], s[18:19], v82, s28, v[104:105]
	global_load_dword v149, v[96:97], off
	global_load_dwordx2 v[142:143], v[100:101], off
	global_load_dwordx2 v[170:171], v[100:101], off offset:32
	global_load_dword v176, v[96:97], off offset:64
	v_mad_u64_u32 v[100:101], s[18:19], v84, s28, v[104:105]
	v_add_u32_e32 v109, v81, v109
	v_lshl_add_u64 v[96:97], s[20:21], 0, v[90:91]
	v_add_u32_e32 v101, v79, v101
	v_lshl_add_u64 v[108:109], v[108:109], 0, v[76:77]
	v_lshl_add_u64 v[96:97], v[96:97], 0, v[76:77]
	v_lshl_add_u64 v[100:101], v[100:101], 0, v[76:77]
	global_load_dwordx2 v[172:173], v[108:109], off
	global_load_dwordx2 v[174:175], v[108:109], off offset:32
	global_load_dwordx2 v[104:105], v[96:97], off
	s_nop 0
	global_load_dwordx2 v[96:97], v[96:97], off offset:32
	s_nop 0
	global_load_dwordx2 v[108:109], v[100:101], off
	s_nop 0
	global_load_dwordx2 v[100:101], v[100:101], off offset:32
	v_and_b32_e32 v102, 0xffff0000, v102
	v_fmac_f32_e32 v102, v123, v71
	v_mul_f32_e32 v70, v106, v70
	v_and_b32_e32 v71, 0xffff0000, v107
	v_mul_f32_e32 v151, v70, v102
	v_mul_f32_e32 v102, 0xbfb8aa3b, v71
	v_exp_f32_e32 v102, v102
	v_add_f32_e32 v70, 1.0, v121
	v_rcp_f32_e32 v70, v70
	v_lshlrev_b32_e32 v106, 16, v103
	v_fmac_f32_e32 v106, v123, v72
	v_add_f32_e32 v72, 1.0, v102
	v_rcp_f32_e32 v72, v72
	v_mul_f32_e32 v70, v70, v120
	v_mul_f32_e32 v152, v70, v106
	v_and_b32_e32 v70, 0xffff0000, v103
	v_fmac_f32_e32 v70, v123, v73
	v_mul_f32_e32 v71, v72, v71
	v_mul_f32_e32 v153, v71, v70
	s_waitcnt vmcnt(14)
	v_lshlrev_b32_e32 v70, 16, v98
	v_mul_f32_e32 v71, 0xbfb8aa3b, v70
	v_exp_f32_e32 v71, v71
	v_and_b32_e32 v73, 0xffff0000, v98
	v_mfma_f32_16x16x32_bf16 v[38:41], v[138:141], v[2:5], v[38:41]
	v_mul_f32_e32 v98, 0xbfb8aa3b, v73
	v_add_f32_e32 v71, 1.0, v71
	v_rcp_f32_e32 v71, v71
	v_exp_f32_e32 v98, v98
	v_lshlrev_b32_e32 v72, 16, v94
	s_nop 2
	v_fmac_f32_e32 v72, v123, v38
	v_mul_f32_e32 v38, v71, v70
	v_mul_f32_e32 v154, v38, v72
	v_add_f32_e32 v38, 1.0, v98
	v_lshlrev_b32_e32 v70, 16, v99
	v_rcp_f32_e32 v38, v38
	v_mul_f32_e32 v71, 0xbfb8aa3b, v70
	v_exp_f32_e32 v71, v71
	v_and_b32_e32 v72, 0xffff0000, v94
	v_fmac_f32_e32 v72, v123, v39
	v_mul_f32_e32 v38, v38, v73
	v_add_f32_e32 v39, 1.0, v71
	v_mul_f32_e32 v155, v38, v72
	v_lshlrev_b32_e32 v38, 16, v95
	v_and_b32_e32 v94, 0xffff0000, v99
	v_rcp_f32_e32 v39, v39
	v_fmac_f32_e32 v38, v123, v40
	v_mul_f32_e32 v40, 0xbfb8aa3b, v94
	v_exp_f32_e32 v40, v40
	v_mul_f32_e32 v39, v39, v70
	v_mul_f32_e32 v156, v39, v38
	v_and_b32_e32 v95, 0xffff0000, v95
	v_add_f32_e32 v38, 1.0, v40
	v_fmac_f32_e32 v95, v123, v41
	v_rcp_f32_e32 v98, v38
	v_cvt_pk_bf16_f32 v38, v50, v51
	v_cvt_pk_bf16_f32 v39, v52, v53
	v_cvt_pk_bf16_f32 v40, v62, v63
	v_cvt_pk_bf16_f32 v41, v64, v65
	v_cvt_pk_bf16_f32 v50, v58, v59
	v_cvt_pk_bf16_f32 v51, v60, v61
	v_cvt_pk_bf16_f32 v52, v46, v47
	v_cvt_pk_bf16_f32 v53, v48, v49
	ds_write_b128 v128, v[38:41] offset:34816
	ds_write_b128 v128, v[50:53] offset:34832
	s_waitcnt lgkmcnt(0)
	s_barrier
	s_add_i32 m0, s98, 0x0
	s_nop 0
	global_load_lds_dwordx4 v239, s[96:97]
	s_add_i32 m0, s98, 0x3f0
	s_nop 0
	global_load_lds_dwordx4 v239, s[96:97] offset:16
	s_add_i32 m0, s98, 0x7e0
	s_nop 0
	global_load_lds_dwordx4 v239, s[96:97] offset:32
	s_add_i32 m0, s98, 0xbd0
	s_nop 0
	global_load_lds_dwordx4 v239, s[96:97] offset:48
	s_add_u32 s96, s96, 0x8000
	s_addc_u32 s97, s97, 0
	ds_read_b128 v[38:41], v129 offset:34816
	ds_read_b128 v[46:49], v129 offset:34880
	ds_read_b128 v[50:53], v129 offset:39168
	ds_read_b128 v[58:61], v129 offset:39232
	ds_read_b128 v[62:65], v129 offset:34944
	ds_read_b128 v[70:73], v129 offset:35008
	ds_read_b128 v[138:141], v129 offset:39296
	ds_read_b128 v[158:161], v129 offset:39360
	v_mul_f32_e32 v94, v98, v94
	v_mul_f32_e32 v157, v94, v95
	v_cvt_pk_bf16_f32 v121, v137, v151
	v_cvt_pk_bf16_f32 v120, v152, v153
	v_cvt_pk_bf16_f32 v124, v154, v155
	v_cvt_pk_bf16_f32 v123, v156, v157
	s_waitcnt lgkmcnt(7)
	v_mfma_f32_16x16x32_bf16 v[162:165], v[38:41], v[30:33], 0
	s_waitcnt vmcnt(9)
	v_lshlrev_b32_e32 v95, 16, v172
	v_mul_f32_e32 v98, 0xbfb8aa3b, v95
	v_exp_f32_e32 v98, v98
	s_waitcnt lgkmcnt(6)
	v_mfma_f32_16x16x32_bf16 v[162:165], v[46:49], v[22:25], v[162:165]
	v_and_b32_e32 v102, 0xffff0000, v172
	v_mul_f32_e32 v103, 0xbfb8aa3b, v102
	v_add_f32_e32 v98, 1.0, v98
	s_waitcnt lgkmcnt(3)
	v_mfma_f32_16x16x32_bf16 v[162:165], v[62:65], v[14:17], v[162:165]
	v_rcp_f32_e32 v98, v98
	v_exp_f32_e32 v103, v103
	v_mul_f32_e32 v94, 0x3fb8aa3b, v149
	v_exp_f32_e32 v94, v94
	s_waitcnt lgkmcnt(2)
	v_mfma_f32_16x16x32_bf16 v[162:165], v[70:73], v[6:9], v[162:165]
	v_mul_f32_e32 v95, v98, v95
	v_add_f32_e32 v98, 1.0, v103
	v_rcp_f32_e32 v98, v98
	v_lshlrev_b32_e32 v99, 16, v142
	v_mfma_f32_16x16x32_bf16 v[38:41], v[38:41], v[26:29], 0
	s_nop 2
	v_fmac_f32_e32 v99, v94, v162
	v_mul_f32_e32 v95, v95, v99
	v_and_b32_e32 v99, 0xffff0000, v142
	v_fmac_f32_e32 v99, v94, v163
	v_mul_f32_e32 v98, v98, v102
	v_mul_f32_e32 v98, v98, v99
	v_lshlrev_b32_e32 v99, 16, v173
	v_mul_f32_e32 v102, 0xbfb8aa3b, v99
	v_mfma_f32_16x16x32_bf16 v[38:41], v[46:49], v[18:21], v[38:41]
	v_exp_f32_e32 v102, v102
	v_lshlrev_b32_e32 v103, 16, v143
	v_fmac_f32_e32 v103, v94, v164
	v_mfma_f32_16x16x32_bf16 v[166:169], v[50:53], v[30:33], 0
	v_add_f32_e32 v102, 1.0, v102
	v_rcp_f32_e32 v102, v102
	v_and_b32_e32 v106, 0xffff0000, v173
	v_mfma_f32_16x16x32_bf16 v[50:53], v[50:53], v[26:29], 0
	v_mul_f32_e32 v107, 0xbfb8aa3b, v106
	s_or_b32 s20, s40, 3
	s_or_b32 s16, s39, s20
	v_mfma_f32_16x16x32_bf16 v[38:41], v[62:65], v[10:13], v[38:41]
	s_lshl_b64 s[18:19], s[16:17], 15
	s_add_u32 s18, s74, s18
	s_addc_u32 s19, s75, s19
	v_mfma_f32_16x16x32_bf16 v[166:169], v[58:61], v[22:25], v[166:169]
	v_cvt_pk_bf16_f32 v42, v42, v43
	v_cvt_pk_bf16_f32 v43, v44, v45
	v_cvt_pk_bf16_f32 v44, v66, v67
	v_mfma_f32_16x16x32_bf16 v[46:49], v[58:61], v[18:21], v[50:53]
	v_exp_f32_e32 v58, v107
	v_and_b32_e32 v60, 0xffff0000, v143
	v_fmac_f32_e32 v60, v94, v165
	v_mfma_f32_16x16x32_bf16 v[70:73], v[70:73], v[2:5], v[38:41]
	v_mul_f32_e32 v50, v102, v99
	v_mul_f32_e32 v59, v50, v103
	v_add_f32_e32 v58, 1.0, v58
	s_waitcnt vmcnt(8)
	v_lshlrev_b32_e32 v38, 16, v174
	v_mul_f32_e32 v39, 0xbfb8aa3b, v38
	v_exp_f32_e32 v39, v39
	s_waitcnt lgkmcnt(1)
	v_mfma_f32_16x16x32_bf16 v[50:53], v[138:141], v[14:17], v[166:169]
	v_and_b32_e32 v41, 0xffff0000, v174
	v_lshlrev_b32_e32 v40, 16, v170
	v_add_f32_e32 v39, 1.0, v39
	v_mfma_f32_16x16x32_bf16 v[46:49], v[138:141], v[10:13], v[46:49]
	v_rcp_f32_e32 v39, v39
	v_rcp_f32_e32 v58, v58
	s_waitcnt vmcnt(5)
	v_lshlrev_b32_e32 v138, 16, v109
	s_waitcnt lgkmcnt(0)
	v_mfma_f32_16x16x32_bf16 v[50:53], v[158:161], v[6:9], v[50:53]
	v_mul_f32_e32 v38, v39, v38
	v_and_b32_e32 v39, 0xffff0000, v170
	v_mul_f32_e32 v58, v58, v106
	v_mfma_f32_16x16x32_bf16 v[62:65], v[158:161], v[2:5], v[46:49]
	v_mul_f32_e32 v58, v58, v60
	s_nop 2
	v_fmac_f32_e32 v40, v94, v50
	v_mul_f32_e32 v38, v38, v40
	v_mul_f32_e32 v46, 0xbfb8aa3b, v41
	v_exp_f32_e32 v46, v46
	v_fmac_f32_e32 v39, v94, v51
	v_mul_f32_e32 v60, v98, v98
	v_fmac_f32_e32 v60, v95, v95
	v_add_f32_e32 v40, 1.0, v46
	v_lshlrev_b32_e32 v46, 16, v175
	v_rcp_f32_e32 v40, v40
	v_mul_f32_e32 v47, 0xbfb8aa3b, v46
	v_exp_f32_e32 v47, v47
	v_lshlrev_b32_e32 v48, 16, v171
	v_mul_f32_e32 v40, v40, v41
	v_and_b32_e32 v41, 0xffff0000, v175
	v_mul_f32_e32 v39, v40, v39
	v_add_f32_e32 v40, 1.0, v47
	v_mul_f32_e32 v47, 0xbfb8aa3b, v41
	v_rcp_f32_e32 v40, v40
	v_exp_f32_e32 v47, v47
	v_cvt_pk_bf16_f32 v149, v38, v39
	v_fmac_f32_e32 v60, v59, v59
	v_mul_f32_e32 v40, v40, v46
	v_add_f32_e32 v46, 1.0, v47
	v_rcp_f32_e32 v46, v46
	v_fmac_f32_e32 v48, v94, v52
	v_and_b32_e32 v47, 0xffff0000, v171
	v_fmac_f32_e32 v60, v58, v58
	v_mul_f32_e32 v41, v46, v41
	v_mul_f32_e32 v46, v39, v39
	v_fmac_f32_e32 v46, v38, v38
	v_mul_f32_e32 v38, 0x3fb8aa3b, v176
	v_exp_f32_e32 v142, v38
	v_lshlrev_b32_e32 v38, 16, v108
	v_mul_f32_e32 v39, 0xbfb8aa3b, v38
	v_exp_f32_e32 v39, v39
	v_mul_f32_e32 v40, v40, v48
	v_fmac_f32_e32 v47, v94, v53
	v_add_f32_e32 v60, v150, v60
	v_mul_f32_e32 v41, v41, v47
	v_fmac_f32_e32 v46, v40, v40
	v_cvt_pk_bf16_f32 v150, v40, v41
	v_lshlrev_b32_e32 v40, 16, v104
	v_fmac_f32_e32 v40, v142, v70
	v_add_f32_e32 v39, 1.0, v39
	v_and_b32_e32 v70, 0xffff0000, v108
	v_fmac_f32_e32 v46, v41, v41
	v_rcp_f32_e32 v39, v39
	v_mul_f32_e32 v41, 0xbfb8aa3b, v70
	v_exp_f32_e32 v41, v41
	v_cvt_pk_bf16_f32 v140, v95, v98
	v_mul_f32_e32 v38, v39, v38
	v_mul_f32_e32 v160, v38, v40
	v_add_f32_e32 v38, 1.0, v41
	v_rcp_f32_e32 v108, v38
	v_mul_f32_e32 v38, 0xbfb8aa3b, v138
	v_exp_f32_e32 v139, v38
	v_lshl_add_u64 v[38:39], s[18:19], 0, v[92:93]
	s_lshl_b64 s[18:19], s[16:17], 9
	s_add_u32 s18, s26, s18
	s_addc_u32 s19, s27, s19
	s_lshl_b32 s16, s20, 7
	s_add_u32 s20, s24, s16
	s_addc_u32 s21, s25, 0
	v_lshl_add_u64 v[38:39], v[38:39], 0, v[74:75]
	s_add_u32 s22, s60, s16
	v_cvt_pk_bf16_f32 v141, v59, v58
	v_lshl_add_u64 v[58:59], v[38:39], 0, s[14:15]
	v_add_co_u32_e32 v38, vcc, s35, v38
	s_addc_u32 s23, s61, 0
	v_lshl_add_u64 v[98:99], s[20:21], 0, v[88:89]
	v_addc_co_u32_e32 v39, vcc, 0, v39, vcc
	v_lshl_add_u64 v[94:95], s[18:19], 0, v[86:87]
	v_mov_b64_e32 v[102:103], s[22:23]
	v_lshl_add_u64 v[98:99], v[98:99], 0, v[76:77]
	v_add_f32_e32 v161, v60, v46
	s_waitcnt vmcnt(0)
	ds_read_b128 v[46:49], v240 offset:0
	s_nop 0
	ds_read_b128 v[38:41], v240 offset:3072
	ds_read_b128 v[50:53], v240 offset:2048
	s_nop 0
	ds_read_b128 v[58:61], v240 offset:1024
	v_mad_u64_u32 v[106:107], s[18:19], v82, s28, v[102:103]
	global_load_dword v166, v[94:95], off
	global_load_dwordx2 v[158:159], v[98:99], off
	global_load_dwordx2 v[182:183], v[98:99], off offset:32
	global_load_dword v185, v[94:95], off offset:64
	v_mad_u64_u32 v[98:99], s[18:19], v84, s28, v[102:103]
	v_add_u32_e32 v107, v81, v107
	v_lshl_add_u64 v[94:95], s[20:21], 0, v[90:91]
	v_add_u32_e32 v99, v79, v99
	v_lshl_add_u64 v[106:107], v[106:107], 0, v[76:77]
	v_lshl_add_u64 v[94:95], v[94:95], 0, v[76:77]
	v_lshl_add_u64 v[98:99], v[98:99], 0, v[76:77]
	global_load_dwordx2 v[190:191], v[106:107], off
	global_load_dwordx2 v[192:193], v[106:107], off offset:32
	global_load_dwordx2 v[102:103], v[94:95], off
	s_nop 0
	global_load_dwordx2 v[94:95], v[94:95], off offset:32
	s_nop 0
	global_load_dwordx2 v[106:107], v[98:99], off
	s_nop 0
	global_load_dwordx2 v[98:99], v[98:99], off offset:32
	v_and_b32_e32 v104, 0xffff0000, v104
	v_fmac_f32_e32 v104, v142, v71
	v_mul_f32_e32 v70, v108, v70
	v_and_b32_e32 v71, 0xffff0000, v109
	v_mul_f32_e32 v167, v70, v104
	v_mul_f32_e32 v104, 0xbfb8aa3b, v71
	v_exp_f32_e32 v104, v104
	v_add_f32_e32 v70, 1.0, v139
	v_rcp_f32_e32 v70, v70
	v_lshlrev_b32_e32 v108, 16, v105
	v_fmac_f32_e32 v108, v142, v72
	v_add_f32_e32 v72, 1.0, v104
	v_rcp_f32_e32 v72, v72
	v_mul_f32_e32 v70, v70, v138
	v_mul_f32_e32 v168, v70, v108
	v_and_b32_e32 v70, 0xffff0000, v105
	v_fmac_f32_e32 v70, v142, v73
	v_mul_f32_e32 v71, v72, v71
	v_mul_f32_e32 v169, v71, v70
	s_waitcnt vmcnt(14)
	v_lshlrev_b32_e32 v70, 16, v100
	v_mul_f32_e32 v71, 0xbfb8aa3b, v70
	v_exp_f32_e32 v71, v71
	v_and_b32_e32 v73, 0xffff0000, v100
	v_mul_f32_e32 v100, 0xbfb8aa3b, v73
	v_exp_f32_e32 v100, v100
	v_add_f32_e32 v71, 1.0, v71
	v_rcp_f32_e32 v71, v71
	v_lshlrev_b32_e32 v72, 16, v96
	v_fmac_f32_e32 v72, v142, v62
	v_cvt_pk_bf16_f32 v45, v68, v69
	v_mul_f32_e32 v62, v71, v70
	v_mul_f32_e32 v170, v62, v72
	v_add_f32_e32 v62, 1.0, v100
	v_lshlrev_b32_e32 v70, 16, v101
	v_rcp_f32_e32 v62, v62
	v_mul_f32_e32 v71, 0xbfb8aa3b, v70
	v_exp_f32_e32 v71, v71
	v_and_b32_e32 v72, 0xffff0000, v96
	v_fmac_f32_e32 v72, v142, v63
	v_mul_f32_e32 v62, v62, v73
	v_add_f32_e32 v63, 1.0, v71
	v_mul_f32_e32 v171, v62, v72
	v_lshlrev_b32_e32 v62, 16, v97
	v_and_b32_e32 v96, 0xffff0000, v101
	v_rcp_f32_e32 v63, v63
	v_fmac_f32_e32 v62, v142, v64
	v_mul_f32_e32 v64, 0xbfb8aa3b, v96
	v_exp_f32_e32 v64, v64
	v_mul_f32_e32 v63, v63, v70
	v_mul_f32_e32 v172, v63, v62
	v_and_b32_e32 v97, 0xffff0000, v97
	v_add_f32_e32 v62, 1.0, v64
	v_cvt_pk_bf16_f32 v54, v54, v55
	v_cvt_pk_bf16_f32 v55, v56, v57
	v_cvt_pk_bf16_f32 v56, v34, v35
	v_cvt_pk_bf16_f32 v57, v36, v37
	v_fmac_f32_e32 v97, v142, v65
	v_rcp_f32_e32 v100, v62
	ds_write_b128 v128, v[42:45] offset:52224
	ds_write_b128 v128, v[54:57] offset:52240
	s_waitcnt lgkmcnt(0)
	s_barrier
	s_add_i32 m0, s98, 0x0
	s_nop 0
	global_load_lds_dwordx4 v239, s[96:97]
	s_add_i32 m0, s98, 0x3f0
	s_nop 0
	global_load_lds_dwordx4 v239, s[96:97] offset:16
	s_add_i32 m0, s98, 0x7e0
	s_nop 0
	global_load_lds_dwordx4 v239, s[96:97] offset:32
	s_add_i32 m0, s98, 0xbd0
	s_nop 0
	global_load_lds_dwordx4 v239, s[96:97] offset:48
	s_add_u32 s96, s96, 0x8000
	s_addc_u32 s97, s97, 0
	ds_read_b128 v[34:37], v129 offset:52224
	ds_read_b128 v[42:45], v129 offset:52288
	ds_read_b128 v[54:57], v129 offset:56576
	ds_read_b128 v[62:65], v129 offset:56640
	ds_read_b128 v[66:69], v129 offset:52352
	ds_read_b128 v[70:73], v129 offset:52416
	ds_read_b128 v[162:165], v129 offset:56704
	ds_read_b128 v[174:177], v129 offset:56768
	v_mul_f32_e32 v96, v100, v96
	v_mul_f32_e32 v173, v96, v97
	v_cvt_pk_bf16_f32 v139, v160, v167
	v_cvt_pk_bf16_f32 v138, v168, v169
	v_cvt_pk_bf16_f32 v143, v170, v171
	v_cvt_pk_bf16_f32 v142, v172, v173
	s_waitcnt lgkmcnt(7)
	v_mfma_f32_16x16x32_bf16 v[178:181], v[34:37], v[30:33], 0
	s_waitcnt vmcnt(9)
	v_lshlrev_b32_e32 v97, 16, v190
	v_mul_f32_e32 v100, 0xbfb8aa3b, v97
	v_exp_f32_e32 v100, v100
	s_waitcnt lgkmcnt(6)
	v_mfma_f32_16x16x32_bf16 v[178:181], v[42:45], v[22:25], v[178:181]
	v_and_b32_e32 v104, 0xffff0000, v190
	v_mul_f32_e32 v105, 0xbfb8aa3b, v104
	v_add_f32_e32 v100, 1.0, v100
	s_waitcnt lgkmcnt(3)
	v_mfma_f32_16x16x32_bf16 v[178:181], v[66:69], v[14:17], v[178:181]
	v_rcp_f32_e32 v100, v100
	v_exp_f32_e32 v105, v105
	v_mul_f32_e32 v96, 0x3fb8aa3b, v166
	v_exp_f32_e32 v96, v96
	s_waitcnt lgkmcnt(2)
	v_mfma_f32_16x16x32_bf16 v[178:181], v[70:73], v[6:9], v[178:181]
	v_mul_f32_e32 v97, v100, v97
	v_add_f32_e32 v100, 1.0, v105
	v_rcp_f32_e32 v100, v100
	v_lshlrev_b32_e32 v101, 16, v158
	v_mfma_f32_16x16x32_bf16 v[34:37], v[34:37], v[26:29], 0
	s_nop 2
	v_fmac_f32_e32 v101, v96, v178
	v_mul_f32_e32 v97, v97, v101
	v_and_b32_e32 v101, 0xffff0000, v158
	v_fmac_f32_e32 v101, v96, v179
	v_mul_f32_e32 v100, v100, v104
	v_mul_f32_e32 v100, v100, v101
	v_lshlrev_b32_e32 v101, 16, v191
	v_mul_f32_e32 v104, 0xbfb8aa3b, v101
	v_mfma_f32_16x16x32_bf16 v[34:37], v[42:45], v[18:21], v[34:37]
	v_exp_f32_e32 v104, v104
	v_lshlrev_b32_e32 v105, 16, v159
	v_fmac_f32_e32 v105, v96, v180
	v_mfma_f32_16x16x32_bf16 v[186:189], v[54:57], v[30:33], 0
	v_add_f32_e32 v104, 1.0, v104
	v_rcp_f32_e32 v104, v104
	v_and_b32_e32 v108, 0xffff0000, v191
	v_mfma_f32_16x16x32_bf16 v[54:57], v[54:57], v[26:29], 0
	v_mul_f32_e32 v109, 0xbfb8aa3b, v108
	s_or_b32 s20, s40, 4
	s_or_b32 s16, s39, s20
	v_mfma_f32_16x16x32_bf16 v[34:37], v[66:69], v[10:13], v[34:37]
	s_lshl_b64 s[18:19], s[16:17], 15
	s_waitcnt vmcnt(5)
	v_lshlrev_b32_e32 v158, 16, v107
	s_add_u32 s18, s74, s18
	v_mfma_f32_16x16x32_bf16 v[186:189], v[62:65], v[22:25], v[186:189]
	s_addc_u32 s19, s75, s19
	v_cvt_pk_bf16_f32 v46, v46, v47
	v_cvt_pk_bf16_f32 v47, v48, v49
	v_mfma_f32_16x16x32_bf16 v[42:45], v[62:65], v[18:21], v[54:57]
	v_exp_f32_e32 v62, v109
	v_and_b32_e32 v64, 0xffff0000, v159
	v_fmac_f32_e32 v64, v96, v181
	v_mfma_f32_16x16x32_bf16 v[70:73], v[70:73], v[2:5], v[34:37]
	v_mul_f32_e32 v54, v104, v101
	v_mul_f32_e32 v63, v54, v105
	v_add_f32_e32 v62, 1.0, v62
	v_lshlrev_b32_e32 v34, 16, v192
	v_mul_f32_e32 v35, 0xbfb8aa3b, v34
	v_exp_f32_e32 v35, v35
	s_waitcnt lgkmcnt(1)
	v_mfma_f32_16x16x32_bf16 v[54:57], v[162:165], v[14:17], v[186:189]
	v_and_b32_e32 v37, 0xffff0000, v192
	v_lshlrev_b32_e32 v36, 16, v182
	v_add_f32_e32 v35, 1.0, v35
	v_mfma_f32_16x16x32_bf16 v[42:45], v[162:165], v[10:13], v[42:45]
	v_rcp_f32_e32 v35, v35
	v_rcp_f32_e32 v62, v62
	v_cvt_pk_bf16_f32 v48, v58, v59
	s_waitcnt lgkmcnt(0)
	v_mfma_f32_16x16x32_bf16 v[54:57], v[174:177], v[6:9], v[54:57]
	v_mul_f32_e32 v34, v35, v34
	v_and_b32_e32 v35, 0xffff0000, v182
	v_mul_f32_e32 v62, v62, v108
	v_mfma_f32_16x16x32_bf16 v[66:69], v[174:177], v[2:5], v[42:45]
	v_mul_f32_e32 v62, v62, v64
	s_nop 2
	v_fmac_f32_e32 v36, v96, v54
	v_mul_f32_e32 v34, v34, v36
	v_mul_f32_e32 v42, 0xbfb8aa3b, v37
	v_exp_f32_e32 v42, v42
	v_fmac_f32_e32 v35, v96, v55
	v_lshlrev_b32_e32 v44, 16, v183
	v_fmac_f32_e32 v44, v96, v56
	v_add_f32_e32 v36, 1.0, v42
	v_lshlrev_b32_e32 v42, 16, v193
	v_rcp_f32_e32 v36, v36
	v_mul_f32_e32 v43, 0xbfb8aa3b, v42
	v_exp_f32_e32 v43, v43
	v_mul_f32_e32 v64, v100, v100
	v_mul_f32_e32 v36, v36, v37
	v_and_b32_e32 v37, 0xffff0000, v193
	v_mul_f32_e32 v35, v36, v35
	v_add_f32_e32 v36, 1.0, v43
	v_mul_f32_e32 v43, 0xbfb8aa3b, v37
	v_rcp_f32_e32 v36, v36
	v_exp_f32_e32 v43, v43
	v_cvt_pk_bf16_f32 v165, v34, v35
	v_fmac_f32_e32 v64, v97, v97
	v_mul_f32_e32 v36, v36, v42
	v_add_f32_e32 v42, 1.0, v43
	v_rcp_f32_e32 v42, v42
	v_and_b32_e32 v43, 0xffff0000, v183
	v_mul_f32_e32 v36, v36, v44
	v_fmac_f32_e32 v43, v96, v57
	v_mul_f32_e32 v37, v42, v37
	v_mul_f32_e32 v42, v35, v35
	v_fmac_f32_e32 v42, v34, v34
	v_mul_f32_e32 v34, 0x3fb8aa3b, v185
	v_exp_f32_e32 v163, v34
	v_lshlrev_b32_e32 v34, 16, v106
	v_mul_f32_e32 v35, 0xbfb8aa3b, v34
	v_exp_f32_e32 v35, v35
	v_mul_f32_e32 v37, v37, v43
	v_fmac_f32_e32 v42, v36, v36
	v_cvt_pk_bf16_f32 v166, v36, v37
	v_lshlrev_b32_e32 v36, 16, v102
	v_fmac_f32_e32 v36, v163, v70
	v_add_f32_e32 v35, 1.0, v35
	v_and_b32_e32 v70, 0xffff0000, v106
	v_fmac_f32_e32 v42, v37, v37
	v_rcp_f32_e32 v35, v35
	v_mul_f32_e32 v37, 0xbfb8aa3b, v70
	v_exp_f32_e32 v37, v37
	v_fmac_f32_e32 v64, v63, v63
	v_mul_f32_e32 v34, v35, v34
	v_mul_f32_e32 v176, v34, v36
	v_add_f32_e32 v34, 1.0, v37
	v_rcp_f32_e32 v106, v34
	v_mul_f32_e32 v34, 0xbfb8aa3b, v158
	v_exp_f32_e32 v159, v34
	v_lshl_add_u64 v[34:35], s[18:19], 0, v[92:93]
	s_lshl_b64 s[18:19], s[16:17], 9
	s_add_u32 s18, s26, s18
	s_addc_u32 s19, s27, s19
	s_lshl_b32 s16, s20, 7
	s_add_u32 s20, s24, s16
	s_addc_u32 s21, s25, 0
	v_fmac_f32_e32 v64, v62, v62
	v_lshl_add_u64 v[34:35], v[34:35], 0, v[74:75]
	s_add_u32 s22, s60, s16
	v_add_f32_e32 v64, v161, v64
	v_cvt_pk_bf16_f32 v161, v97, v100
	v_cvt_pk_bf16_f32 v162, v63, v62
	v_lshl_add_u64 v[62:63], v[34:35], 0, s[14:15]
	v_add_co_u32_e32 v34, vcc, s35, v34
	s_addc_u32 s23, s61, 0
	v_lshl_add_u64 v[100:101], s[20:21], 0, v[88:89]
	v_addc_co_u32_e32 v35, vcc, 0, v35, vcc
	v_lshl_add_u64 v[96:97], s[18:19], 0, v[86:87]
	v_mov_b64_e32 v[104:105], s[22:23]
	v_lshl_add_u64 v[100:101], v[100:101], 0, v[76:77]
	v_add_f32_e32 v177, v64, v42
	s_waitcnt vmcnt(0)
	ds_read_b128 v[42:45], v240 offset:0
	s_nop 0
	ds_read_b128 v[34:37], v240 offset:3072
	ds_read_b128 v[54:57], v240 offset:2048
	s_nop 0
	ds_read_b128 v[62:65], v240 offset:1024
	v_mad_u64_u32 v[108:109], s[18:19], v82, s28, v[104:105]
	global_load_dword v180, v[96:97], off
	global_load_dwordx2 v[174:175], v[100:101], off
	global_load_dwordx2 v[178:179], v[100:101], off offset:32
	global_load_dword v189, v[96:97], off offset:64
	v_mad_u64_u32 v[100:101], s[18:19], v84, s28, v[104:105]
	v_add_u32_e32 v109, v81, v109
	v_lshl_add_u64 v[96:97], s[20:21], 0, v[90:91]
	v_add_u32_e32 v101, v79, v101
	v_lshl_add_u64 v[108:109], v[108:109], 0, v[76:77]
	v_lshl_add_u64 v[96:97], v[96:97], 0, v[76:77]
	v_lshl_add_u64 v[100:101], v[100:101], 0, v[76:77]
	global_load_dwordx2 v[206:207], v[108:109], off
	global_load_dwordx2 v[208:209], v[108:109], off offset:32
	global_load_dwordx2 v[104:105], v[96:97], off
	s_nop 0
	global_load_dwordx2 v[96:97], v[96:97], off offset:32
	s_nop 0
	global_load_dwordx2 v[108:109], v[100:101], off
	s_nop 0
	global_load_dwordx2 v[100:101], v[100:101], off offset:32
	v_and_b32_e32 v102, 0xffff0000, v102
	v_fmac_f32_e32 v102, v163, v71
	v_mul_f32_e32 v70, v106, v70
	v_and_b32_e32 v71, 0xffff0000, v107
	v_mul_f32_e32 v181, v70, v102
	v_mul_f32_e32 v102, 0xbfb8aa3b, v71
	v_exp_f32_e32 v102, v102
	v_add_f32_e32 v70, 1.0, v159
	v_rcp_f32_e32 v70, v70
	v_lshlrev_b32_e32 v106, 16, v103
	v_fmac_f32_e32 v106, v163, v72
	v_add_f32_e32 v72, 1.0, v102
	v_rcp_f32_e32 v72, v72
	v_mul_f32_e32 v70, v70, v158
	v_mul_f32_e32 v182, v70, v106
	v_and_b32_e32 v70, 0xffff0000, v103
	v_fmac_f32_e32 v70, v163, v73
	v_mul_f32_e32 v71, v72, v71
	v_mul_f32_e32 v183, v71, v70
	s_waitcnt vmcnt(14)
	v_lshlrev_b32_e32 v70, 16, v98
	v_mul_f32_e32 v71, 0xbfb8aa3b, v70
	v_exp_f32_e32 v71, v71
	v_and_b32_e32 v73, 0xffff0000, v98
	v_mul_f32_e32 v98, 0xbfb8aa3b, v73
	v_exp_f32_e32 v98, v98
	v_add_f32_e32 v71, 1.0, v71
	v_rcp_f32_e32 v71, v71
	v_lshlrev_b32_e32 v72, 16, v94
	v_fmac_f32_e32 v72, v163, v66
	v_cvt_pk_bf16_f32 v49, v60, v61
	v_mul_f32_e32 v66, v71, v70
	v_mul_f32_e32 v185, v66, v72
	v_add_f32_e32 v66, 1.0, v98
	v_lshlrev_b32_e32 v70, 16, v99
	v_rcp_f32_e32 v66, v66
	v_mul_f32_e32 v71, 0xbfb8aa3b, v70
	v_exp_f32_e32 v71, v71
	v_and_b32_e32 v72, 0xffff0000, v94
	v_fmac_f32_e32 v72, v163, v67
	v_mul_f32_e32 v66, v66, v73
	v_add_f32_e32 v67, 1.0, v71
	v_mul_f32_e32 v186, v66, v72
	v_lshlrev_b32_e32 v66, 16, v95
	v_and_b32_e32 v94, 0xffff0000, v99
	v_rcp_f32_e32 v67, v67
	v_fmac_f32_e32 v66, v163, v68
	v_mul_f32_e32 v68, 0xbfb8aa3b, v94
	v_exp_f32_e32 v68, v68
	v_mul_f32_e32 v67, v67, v70
	v_mul_f32_e32 v187, v67, v66
	v_and_b32_e32 v95, 0xffff0000, v95
	v_add_f32_e32 v66, 1.0, v68
	v_cvt_pk_bf16_f32 v50, v50, v51
	v_cvt_pk_bf16_f32 v51, v52, v53
	v_cvt_pk_bf16_f32 v52, v38, v39
	v_cvt_pk_bf16_f32 v53, v40, v41
	v_fmac_f32_e32 v95, v163, v69
	v_rcp_f32_e32 v98, v66
	ds_write_b128 v128, v[46:49] offset:34816
	ds_write_b128 v128, v[50:53] offset:34832
	s_waitcnt lgkmcnt(0)
	s_barrier
	s_add_i32 m0, s98, 0x0
	s_nop 0
	global_load_lds_dwordx4 v239, s[96:97]
	s_add_i32 m0, s98, 0x3f0
	s_nop 0
	global_load_lds_dwordx4 v239, s[96:97] offset:16
	s_add_i32 m0, s98, 0x7e0
	s_nop 0
	global_load_lds_dwordx4 v239, s[96:97] offset:32
	s_add_i32 m0, s98, 0xbd0
	s_nop 0
	global_load_lds_dwordx4 v239, s[96:97] offset:48
	s_add_u32 s96, s96, 0x8000
	s_addc_u32 s97, s97, 0
	ds_read_b128 v[38:41], v129 offset:34816
	ds_read_b128 v[46:49], v129 offset:34880
	ds_read_b128 v[50:53], v129 offset:39168
	ds_read_b128 v[58:61], v129 offset:39232
	ds_read_b128 v[66:69], v129 offset:34944
	ds_read_b128 v[70:73], v129 offset:35008
	ds_read_b128 v[190:193], v129 offset:39296
	ds_read_b128 v[194:197], v129 offset:39360
	v_mul_f32_e32 v94, v98, v94
	v_mul_f32_e32 v188, v94, v95
	v_cvt_pk_bf16_f32 v159, v176, v181
	v_cvt_pk_bf16_f32 v158, v182, v183
	v_cvt_pk_bf16_f32 v164, v185, v186
	v_cvt_pk_bf16_f32 v163, v187, v188
	s_waitcnt lgkmcnt(7)
	v_mfma_f32_16x16x32_bf16 v[198:201], v[38:41], v[30:33], 0
	s_waitcnt vmcnt(9)
	v_lshlrev_b32_e32 v95, 16, v206
	v_mul_f32_e32 v98, 0xbfb8aa3b, v95
	v_exp_f32_e32 v98, v98
	s_waitcnt lgkmcnt(6)
	v_mfma_f32_16x16x32_bf16 v[198:201], v[46:49], v[22:25], v[198:201]
	v_and_b32_e32 v102, 0xffff0000, v206
	v_mul_f32_e32 v103, 0xbfb8aa3b, v102
	v_add_f32_e32 v98, 1.0, v98
	s_waitcnt lgkmcnt(3)
	v_mfma_f32_16x16x32_bf16 v[198:201], v[66:69], v[14:17], v[198:201]
	v_rcp_f32_e32 v98, v98
	v_exp_f32_e32 v103, v103
	v_mul_f32_e32 v94, 0x3fb8aa3b, v180
	v_exp_f32_e32 v94, v94
	s_waitcnt lgkmcnt(2)
	v_mfma_f32_16x16x32_bf16 v[198:201], v[70:73], v[6:9], v[198:201]
	v_mul_f32_e32 v95, v98, v95
	v_add_f32_e32 v98, 1.0, v103
	v_rcp_f32_e32 v98, v98
	v_lshlrev_b32_e32 v99, 16, v174
	v_mfma_f32_16x16x32_bf16 v[38:41], v[38:41], v[26:29], 0
	s_nop 2
	v_fmac_f32_e32 v99, v94, v198
	v_mul_f32_e32 v95, v95, v99
	v_and_b32_e32 v99, 0xffff0000, v174
	v_fmac_f32_e32 v99, v94, v199
	v_mul_f32_e32 v98, v98, v102
	v_mul_f32_e32 v98, v98, v99
	v_lshlrev_b32_e32 v99, 16, v207
	v_mul_f32_e32 v102, 0xbfb8aa3b, v99
	v_mfma_f32_16x16x32_bf16 v[38:41], v[46:49], v[18:21], v[38:41]
	v_exp_f32_e32 v102, v102
	v_lshlrev_b32_e32 v103, 16, v175
	v_fmac_f32_e32 v103, v94, v200
	v_mfma_f32_16x16x32_bf16 v[202:205], v[50:53], v[30:33], 0
	v_add_f32_e32 v102, 1.0, v102
	v_rcp_f32_e32 v102, v102
	v_and_b32_e32 v106, 0xffff0000, v207
	v_mfma_f32_16x16x32_bf16 v[50:53], v[50:53], v[26:29], 0
	v_mul_f32_e32 v107, 0xbfb8aa3b, v106
	s_or_b32 s20, s40, 5
	s_or_b32 s16, s39, s20
	v_mfma_f32_16x16x32_bf16 v[38:41], v[66:69], v[10:13], v[38:41]
	s_lshl_b64 s[18:19], s[16:17], 15
	s_add_u32 s18, s74, s18
	s_addc_u32 s19, s75, s19
	v_mfma_f32_16x16x32_bf16 v[202:205], v[58:61], v[22:25], v[202:205]
	v_cvt_pk_bf16_f32 v174, v95, v98
	v_cvt_pk_bf16_f32 v42, v42, v43
	v_cvt_pk_bf16_f32 v43, v44, v45
	v_mfma_f32_16x16x32_bf16 v[46:49], v[58:61], v[18:21], v[50:53]
	v_exp_f32_e32 v58, v107
	v_and_b32_e32 v60, 0xffff0000, v175
	v_fmac_f32_e32 v60, v94, v201
	v_mfma_f32_16x16x32_bf16 v[70:73], v[70:73], v[2:5], v[38:41]
	v_mul_f32_e32 v50, v102, v99
	v_mul_f32_e32 v59, v50, v103
	v_add_f32_e32 v58, 1.0, v58
	s_waitcnt vmcnt(8)
	v_lshlrev_b32_e32 v38, 16, v208
	v_mul_f32_e32 v39, 0xbfb8aa3b, v38
	v_exp_f32_e32 v39, v39
	s_waitcnt lgkmcnt(1)
	v_mfma_f32_16x16x32_bf16 v[50:53], v[190:193], v[14:17], v[202:205]
	v_and_b32_e32 v41, 0xffff0000, v208
	v_lshlrev_b32_e32 v40, 16, v178
	v_add_f32_e32 v39, 1.0, v39
	v_mfma_f32_16x16x32_bf16 v[46:49], v[190:193], v[10:13], v[46:49]
	v_rcp_f32_e32 v39, v39
	v_rcp_f32_e32 v58, v58
	v_cvt_pk_bf16_f32 v44, v62, v63
	s_waitcnt lgkmcnt(0)
	v_mfma_f32_16x16x32_bf16 v[50:53], v[194:197], v[6:9], v[50:53]
	v_mul_f32_e32 v38, v39, v38
	v_and_b32_e32 v39, 0xffff0000, v178
	v_mul_f32_e32 v58, v58, v106
	v_mfma_f32_16x16x32_bf16 v[66:69], v[194:197], v[2:5], v[46:49]
	v_mul_f32_e32 v58, v58, v60
	s_nop 2
	v_fmac_f32_e32 v40, v94, v50
	v_mul_f32_e32 v38, v38, v40
	v_mul_f32_e32 v46, 0xbfb8aa3b, v41
	v_exp_f32_e32 v46, v46
	v_fmac_f32_e32 v39, v94, v51
	v_mul_f32_e32 v60, v98, v98
	v_fmac_f32_e32 v60, v95, v95
	v_add_f32_e32 v40, 1.0, v46
	v_lshlrev_b32_e32 v46, 16, v209
	v_rcp_f32_e32 v40, v40
	v_mul_f32_e32 v47, 0xbfb8aa3b, v46
	v_exp_f32_e32 v47, v47
	v_fmac_f32_e32 v60, v59, v59
	v_mul_f32_e32 v40, v40, v41
	v_and_b32_e32 v41, 0xffff0000, v209
	v_mul_f32_e32 v39, v40, v39
	v_add_f32_e32 v40, 1.0, v47
	v_mul_f32_e32 v47, 0xbfb8aa3b, v41
	v_rcp_f32_e32 v40, v40
	v_exp_f32_e32 v47, v47
	v_fmac_f32_e32 v60, v58, v58
	v_lshlrev_b32_e32 v48, 16, v179
	v_mul_f32_e32 v40, v40, v46
	v_add_f32_e32 v46, 1.0, v47
	v_rcp_f32_e32 v46, v46
	v_and_b32_e32 v47, 0xffff0000, v179
	v_cvt_pk_bf16_f32 v179, v38, v39
	v_add_f32_e32 v60, v177, v60
	v_mul_f32_e32 v41, v46, v41
	v_mul_f32_e32 v46, v39, v39
	v_fmac_f32_e32 v46, v38, v38
	v_mul_f32_e32 v38, 0x3fb8aa3b, v189
	v_exp_f32_e32 v177, v38
	s_waitcnt vmcnt(5)
	v_lshlrev_b32_e32 v38, 16, v108
	v_mul_f32_e32 v39, 0xbfb8aa3b, v38
	v_exp_f32_e32 v39, v39
	v_fmac_f32_e32 v48, v94, v52
	v_mul_f32_e32 v40, v40, v48
	v_fmac_f32_e32 v47, v94, v53
	v_mul_f32_e32 v41, v41, v47
	v_fmac_f32_e32 v46, v40, v40
	v_cvt_pk_bf16_f32 v180, v40, v41
	v_lshlrev_b32_e32 v40, 16, v104
	v_fmac_f32_e32 v40, v177, v70
	v_add_f32_e32 v39, 1.0, v39
	v_and_b32_e32 v70, 0xffff0000, v108
	v_fmac_f32_e32 v46, v41, v41
	v_rcp_f32_e32 v39, v39
	v_mul_f32_e32 v41, 0xbfb8aa3b, v70
	v_exp_f32_e32 v41, v41
	v_lshlrev_b32_e32 v178, 16, v109
	v_mul_f32_e32 v38, v39, v38
	v_mul_f32_e32 v191, v38, v40
	v_add_f32_e32 v38, 1.0, v41
	v_rcp_f32_e32 v108, v38
	v_mul_f32_e32 v38, 0xbfb8aa3b, v178
	v_exp_f32_e32 v189, v38
	v_lshl_add_u64 v[38:39], s[18:19], 0, v[92:93]
	s_lshl_b64 s[18:19], s[16:17], 9
	s_add_u32 s18, s26, s18
	s_addc_u32 s19, s27, s19
	s_lshl_b32 s16, s20, 7
	s_add_u32 s20, s24, s16
	s_addc_u32 s21, s25, 0
	v_lshl_add_u64 v[38:39], v[38:39], 0, v[74:75]
	s_add_u32 s22, s60, s16
	v_cvt_pk_bf16_f32 v175, v59, v58
	v_lshl_add_u64 v[58:59], v[38:39], 0, s[14:15]
	v_add_co_u32_e32 v38, vcc, s35, v38
	s_addc_u32 s23, s61, 0
	v_lshl_add_u64 v[98:99], s[20:21], 0, v[88:89]
	v_addc_co_u32_e32 v39, vcc, 0, v39, vcc
	v_lshl_add_u64 v[94:95], s[18:19], 0, v[86:87]
	v_mov_b64_e32 v[102:103], s[22:23]
	v_lshl_add_u64 v[98:99], v[98:99], 0, v[76:77]
	v_add_f32_e32 v190, v60, v46
	s_waitcnt vmcnt(0)
	ds_read_b128 v[46:49], v240 offset:0
	s_nop 0
	ds_read_b128 v[38:41], v240 offset:3072
	ds_read_b128 v[50:53], v240 offset:2048
	s_nop 0
	ds_read_b128 v[58:61], v240 offset:1024
	v_mad_u64_u32 v[106:107], s[18:19], v82, s28, v[102:103]
	global_load_dword v201, v[94:95], off
	global_load_dwordx2 v[192:193], v[98:99], off
	global_load_dwordx2 v[218:219], v[98:99], off offset:32
	global_load_dword v224, v[94:95], off offset:64
	v_mad_u64_u32 v[98:99], s[18:19], v84, s28, v[102:103]
	v_add_u32_e32 v107, v81, v107
	v_lshl_add_u64 v[94:95], s[20:21], 0, v[90:91]
	v_add_u32_e32 v99, v79, v99
	v_lshl_add_u64 v[106:107], v[106:107], 0, v[76:77]
	v_lshl_add_u64 v[94:95], v[94:95], 0, v[76:77]
	v_lshl_add_u64 v[98:99], v[98:99], 0, v[76:77]
	global_load_dwordx2 v[220:221], v[106:107], off
	global_load_dwordx2 v[222:223], v[106:107], off offset:32
	global_load_dwordx2 v[102:103], v[94:95], off
	s_nop 0
	global_load_dwordx2 v[94:95], v[94:95], off offset:32
	s_nop 0
	global_load_dwordx2 v[106:107], v[98:99], off
	s_nop 0
	global_load_dwordx2 v[98:99], v[98:99], off offset:32
	v_and_b32_e32 v104, 0xffff0000, v104
	v_fmac_f32_e32 v104, v177, v71
	v_mul_f32_e32 v70, v108, v70
	v_and_b32_e32 v71, 0xffff0000, v109
	v_mul_f32_e32 v194, v70, v104
	v_mul_f32_e32 v104, 0xbfb8aa3b, v71
	v_exp_f32_e32 v104, v104
	v_add_f32_e32 v70, 1.0, v189
	v_rcp_f32_e32 v70, v70
	v_lshlrev_b32_e32 v108, 16, v105
	v_fmac_f32_e32 v108, v177, v72
	v_add_f32_e32 v72, 1.0, v104
	v_rcp_f32_e32 v72, v72
	v_mul_f32_e32 v70, v70, v178
	v_mul_f32_e32 v195, v70, v108
	v_and_b32_e32 v70, 0xffff0000, v105
	v_fmac_f32_e32 v70, v177, v73
	v_mul_f32_e32 v71, v72, v71
	v_mul_f32_e32 v196, v71, v70
	s_waitcnt vmcnt(14)
	v_lshlrev_b32_e32 v70, 16, v100
	v_mul_f32_e32 v71, 0xbfb8aa3b, v70
	v_exp_f32_e32 v71, v71
	v_and_b32_e32 v73, 0xffff0000, v100
	v_mul_f32_e32 v100, 0xbfb8aa3b, v73
	v_exp_f32_e32 v100, v100
	v_add_f32_e32 v71, 1.0, v71
	v_rcp_f32_e32 v71, v71
	v_lshlrev_b32_e32 v72, 16, v96
	v_fmac_f32_e32 v72, v177, v66
	v_cvt_pk_bf16_f32 v45, v64, v65
	v_mul_f32_e32 v66, v71, v70
	v_mul_f32_e32 v197, v66, v72
	v_add_f32_e32 v66, 1.0, v100
	v_lshlrev_b32_e32 v70, 16, v101
	v_rcp_f32_e32 v66, v66
	v_mul_f32_e32 v71, 0xbfb8aa3b, v70
	v_exp_f32_e32 v71, v71
	v_and_b32_e32 v72, 0xffff0000, v96
	v_fmac_f32_e32 v72, v177, v67
	v_mul_f32_e32 v66, v66, v73
	v_add_f32_e32 v67, 1.0, v71
	v_mul_f32_e32 v198, v66, v72
	v_lshlrev_b32_e32 v66, 16, v97
	v_and_b32_e32 v96, 0xffff0000, v101
	v_rcp_f32_e32 v67, v67
	v_fmac_f32_e32 v66, v177, v68
	v_mul_f32_e32 v68, 0xbfb8aa3b, v96
	v_exp_f32_e32 v68, v68
	v_mul_f32_e32 v67, v67, v70
	v_mul_f32_e32 v199, v67, v66
	v_and_b32_e32 v97, 0xffff0000, v97
	v_add_f32_e32 v66, 1.0, v68
	v_cvt_pk_bf16_f32 v54, v54, v55
	v_cvt_pk_bf16_f32 v55, v56, v57
	v_cvt_pk_bf16_f32 v56, v34, v35
	v_cvt_pk_bf16_f32 v57, v36, v37
	v_fmac_f32_e32 v97, v177, v69
	v_rcp_f32_e32 v100, v66
	ds_write_b128 v128, v[42:45] offset:52224
	ds_write_b128 v128, v[54:57] offset:52240
	s_waitcnt lgkmcnt(0)
	s_barrier
	s_add_i32 m0, s98, 0x0
	s_nop 0
	global_load_lds_dwordx4 v239, s[96:97]
	s_add_i32 m0, s98, 0x3f0
	s_nop 0
	global_load_lds_dwordx4 v239, s[96:97] offset:16
	s_add_i32 m0, s98, 0x7e0
	s_nop 0
	global_load_lds_dwordx4 v239, s[96:97] offset:32
	s_add_i32 m0, s98, 0xbd0
	s_nop 0
	global_load_lds_dwordx4 v239, s[96:97] offset:48
	s_add_u32 s96, s96, 0x8000
	s_addc_u32 s97, s97, 0
	ds_read_b128 v[34:37], v129 offset:52224
	ds_read_b128 v[42:45], v129 offset:52288
	ds_read_b128 v[54:57], v129 offset:56576
	ds_read_b128 v[62:65], v129 offset:56640
	ds_read_b128 v[66:69], v129 offset:52352
	ds_read_b128 v[70:73], v129 offset:52416
	ds_read_b128 v[202:205], v129 offset:56704
	ds_read_b128 v[206:209], v129 offset:56768
	v_mul_f32_e32 v96, v100, v96
	v_mul_f32_e32 v200, v96, v97
	v_cvt_pk_bf16_f32 v109, v191, v194
	v_cvt_pk_bf16_f32 v108, v195, v196
	v_cvt_pk_bf16_f32 v178, v197, v198
	v_cvt_pk_bf16_f32 v177, v199, v200
	s_waitcnt lgkmcnt(7)
	v_mfma_f32_16x16x32_bf16 v[210:213], v[34:37], v[30:33], 0
	s_waitcnt vmcnt(9)
	v_lshlrev_b32_e32 v97, 16, v220
	v_mul_f32_e32 v100, 0xbfb8aa3b, v97
	v_exp_f32_e32 v100, v100
	s_waitcnt lgkmcnt(6)
	v_mfma_f32_16x16x32_bf16 v[210:213], v[42:45], v[22:25], v[210:213]
	v_and_b32_e32 v104, 0xffff0000, v220
	v_mul_f32_e32 v105, 0xbfb8aa3b, v104
	v_add_f32_e32 v100, 1.0, v100
	s_waitcnt lgkmcnt(3)
	v_mfma_f32_16x16x32_bf16 v[210:213], v[66:69], v[14:17], v[210:213]
	v_rcp_f32_e32 v100, v100
	v_exp_f32_e32 v105, v105
	v_mul_f32_e32 v96, 0x3fb8aa3b, v201
	v_exp_f32_e32 v96, v96
	s_waitcnt lgkmcnt(2)
	v_mfma_f32_16x16x32_bf16 v[210:213], v[70:73], v[6:9], v[210:213]
	v_mul_f32_e32 v97, v100, v97
	v_add_f32_e32 v100, 1.0, v105
	v_rcp_f32_e32 v100, v100
	v_lshlrev_b32_e32 v101, 16, v192
	v_mfma_f32_16x16x32_bf16 v[34:37], v[34:37], v[26:29], 0
	s_nop 2
	v_fmac_f32_e32 v101, v96, v210
	v_mul_f32_e32 v97, v97, v101
	v_and_b32_e32 v101, 0xffff0000, v192
	v_fmac_f32_e32 v101, v96, v211
	v_mul_f32_e32 v100, v100, v104
	v_mul_f32_e32 v100, v100, v101
	v_lshlrev_b32_e32 v101, 16, v221
	v_mul_f32_e32 v104, 0xbfb8aa3b, v101
	v_mfma_f32_16x16x32_bf16 v[34:37], v[42:45], v[18:21], v[34:37]
	v_exp_f32_e32 v104, v104
	v_lshlrev_b32_e32 v105, 16, v193
	v_fmac_f32_e32 v105, v96, v212
	v_mfma_f32_16x16x32_bf16 v[214:217], v[54:57], v[30:33], 0
	v_add_f32_e32 v104, 1.0, v104
	v_rcp_f32_e32 v104, v104
	v_and_b32_e32 v189, 0xffff0000, v221
	v_mfma_f32_16x16x32_bf16 v[54:57], v[54:57], v[26:29], 0
	v_mul_f32_e32 v192, 0xbfb8aa3b, v189
	s_or_b32 s20, s40, 6
	s_or_b32 s16, s39, s20
	v_mfma_f32_16x16x32_bf16 v[34:37], v[66:69], v[10:13], v[34:37]
	s_lshl_b64 s[18:19], s[16:17], 15
	s_add_u32 s18, s74, s18
	s_addc_u32 s19, s75, s19
	v_mfma_f32_16x16x32_bf16 v[214:217], v[62:65], v[22:25], v[214:217]
	v_cvt_pk_bf16_f32 v46, v46, v47
	v_cvt_pk_bf16_f32 v47, v48, v49
	v_cvt_pk_bf16_f32 v48, v58, v59
	v_mfma_f32_16x16x32_bf16 v[42:45], v[62:65], v[18:21], v[54:57]
	v_exp_f32_e32 v62, v192
	v_and_b32_e32 v64, 0xffff0000, v193
	v_fmac_f32_e32 v64, v96, v213
	v_mfma_f32_16x16x32_bf16 v[70:73], v[70:73], v[2:5], v[34:37]
	v_mul_f32_e32 v54, v104, v101
	v_mul_f32_e32 v63, v54, v105
	v_add_f32_e32 v62, 1.0, v62
	s_waitcnt vmcnt(8)
	v_lshlrev_b32_e32 v34, 16, v222
	v_mul_f32_e32 v35, 0xbfb8aa3b, v34
	v_exp_f32_e32 v35, v35
	s_waitcnt lgkmcnt(1)
	v_mfma_f32_16x16x32_bf16 v[54:57], v[202:205], v[14:17], v[214:217]
	v_and_b32_e32 v37, 0xffff0000, v222
	v_lshlrev_b32_e32 v36, 16, v218
	v_add_f32_e32 v35, 1.0, v35
	v_mfma_f32_16x16x32_bf16 v[42:45], v[202:205], v[10:13], v[42:45]
	v_rcp_f32_e32 v35, v35
	v_rcp_f32_e32 v62, v62
	s_waitcnt vmcnt(5)
	v_lshlrev_b32_e32 v204, 16, v107
	s_waitcnt lgkmcnt(0)
	v_mfma_f32_16x16x32_bf16 v[54:57], v[206:209], v[6:9], v[54:57]
	v_mul_f32_e32 v34, v35, v34
	v_and_b32_e32 v35, 0xffff0000, v218
	v_mul_f32_e32 v62, v62, v189
	v_mfma_f32_16x16x32_bf16 v[66:69], v[206:209], v[2:5], v[42:45]
	v_mul_f32_e32 v62, v62, v64
	s_nop 2
	v_fmac_f32_e32 v36, v96, v54
	v_mul_f32_e32 v34, v34, v36
	v_mul_f32_e32 v42, 0xbfb8aa3b, v37
	v_exp_f32_e32 v42, v42
	v_fmac_f32_e32 v35, v96, v55
	v_lshlrev_b32_e32 v44, 16, v219
	v_fmac_f32_e32 v44, v96, v56
	v_add_f32_e32 v36, 1.0, v42
	v_lshlrev_b32_e32 v42, 16, v223
	v_rcp_f32_e32 v36, v36
	v_mul_f32_e32 v43, 0xbfb8aa3b, v42
	v_exp_f32_e32 v43, v43
	v_mul_f32_e32 v64, v100, v100
	v_mul_f32_e32 v36, v36, v37
	v_and_b32_e32 v37, 0xffff0000, v223
	v_mul_f32_e32 v35, v36, v35
	v_add_f32_e32 v36, 1.0, v43
	v_mul_f32_e32 v43, 0xbfb8aa3b, v37
	v_rcp_f32_e32 v36, v36
	v_exp_f32_e32 v43, v43
	v_cvt_pk_bf16_f32 v192, v34, v35
	v_fmac_f32_e32 v64, v97, v97
	v_mul_f32_e32 v36, v36, v42
	v_add_f32_e32 v42, 1.0, v43
	v_rcp_f32_e32 v42, v42
	v_and_b32_e32 v43, 0xffff0000, v219
	v_mul_f32_e32 v36, v36, v44
	v_fmac_f32_e32 v43, v96, v57
	v_mul_f32_e32 v37, v42, v37
	v_mul_f32_e32 v42, v35, v35
	v_fmac_f32_e32 v42, v34, v34
	v_mul_f32_e32 v34, 0x3fb8aa3b, v224
	v_exp_f32_e32 v202, v34
	v_lshlrev_b32_e32 v34, 16, v106
	v_mul_f32_e32 v35, 0xbfb8aa3b, v34
	v_exp_f32_e32 v35, v35
	v_mul_f32_e32 v37, v37, v43
	v_fmac_f32_e32 v42, v36, v36
	v_cvt_pk_bf16_f32 v193, v36, v37
	v_lshlrev_b32_e32 v36, 16, v102
	v_fmac_f32_e32 v36, v202, v70
	v_add_f32_e32 v35, 1.0, v35
	v_and_b32_e32 v70, 0xffff0000, v106
	v_fmac_f32_e32 v42, v37, v37
	v_rcp_f32_e32 v35, v35
	v_mul_f32_e32 v37, 0xbfb8aa3b, v70
	v_exp_f32_e32 v37, v37
	v_fmac_f32_e32 v64, v63, v63
	v_mul_f32_e32 v34, v35, v34
	v_mul_f32_e32 v106, v34, v36
	v_add_f32_e32 v34, 1.0, v37
	v_rcp_f32_e32 v203, v34
	v_mul_f32_e32 v34, 0xbfb8aa3b, v204
	v_exp_f32_e32 v205, v34
	v_lshl_add_u64 v[34:35], s[18:19], 0, v[92:93]
	s_lshl_b64 s[18:19], s[16:17], 9
	s_add_u32 s18, s26, s18
	s_addc_u32 s19, s27, s19
	s_lshl_b32 s16, s20, 7
	s_add_u32 s20, s24, s16
	s_addc_u32 s21, s25, 0
	v_fmac_f32_e32 v64, v62, v62
	v_lshl_add_u64 v[34:35], v[34:35], 0, v[74:75]
	s_add_u32 s22, s60, s16
	v_add_f32_e32 v64, v190, v64
	v_cvt_pk_bf16_f32 v189, v97, v100
	v_cvt_pk_bf16_f32 v190, v63, v62
	v_lshl_add_u64 v[62:63], v[34:35], 0, s[14:15]
	v_add_co_u32_e32 v34, vcc, s35, v34
	s_addc_u32 s23, s61, 0
	v_lshl_add_u64 v[96:97], s[20:21], 0, v[88:89]
	v_addc_co_u32_e32 v35, vcc, 0, v35, vcc
	v_lshl_add_u64 v[92:93], s[18:19], 0, v[86:87]
	v_mov_b64_e32 v[100:101], s[22:23]
	v_lshl_add_u64 v[96:97], v[96:97], 0, v[76:77]
	v_add_f32_e32 v201, v64, v42
	s_waitcnt vmcnt(0)
	ds_read_b128 v[42:45], v240 offset:0
	s_nop 0
	ds_read_b128 v[34:37], v240 offset:3072
	ds_read_b128 v[54:57], v240 offset:2048
	s_nop 0
	ds_read_b128 v[62:65], v240 offset:1024
	v_mad_u64_u32 v[104:105], s[18:19], v82, s28, v[100:101]
	global_load_dword v222, v[92:93], off
	global_load_dwordx2 v[230:231], v[96:97], off
	global_load_dwordx2 v[232:233], v[96:97], off offset:32
	global_load_dword v238, v[92:93], off offset:64
	v_mad_u64_u32 v[96:97], s[18:19], v84, s28, v[100:101]
	v_add_u32_e32 v105, v81, v105
	v_lshl_add_u64 v[92:93], s[20:21], 0, v[90:91]
	v_add_u32_e32 v97, v79, v97
	v_lshl_add_u64 v[104:105], v[104:105], 0, v[76:77]
	v_lshl_add_u64 v[92:93], v[92:93], 0, v[76:77]
	v_lshl_add_u64 v[96:97], v[96:97], 0, v[76:77]
	global_load_dwordx2 v[234:235], v[104:105], off
	global_load_dwordx2 v[236:237], v[104:105], off offset:32
	global_load_dwordx2 v[100:101], v[92:93], off
	s_nop 0
	global_load_dwordx2 v[92:93], v[92:93], off offset:32
	s_nop 0
	global_load_dwordx2 v[104:105], v[96:97], off
	s_nop 0
	global_load_dwordx2 v[96:97], v[96:97], off offset:32
	v_and_b32_e32 v102, 0xffff0000, v102
	v_fmac_f32_e32 v102, v202, v71
	v_mul_f32_e32 v70, v203, v70
	v_and_b32_e32 v71, 0xffff0000, v107
	v_mul_f32_e32 v74, v70, v102
	v_mul_f32_e32 v102, 0xbfb8aa3b, v71
	v_exp_f32_e32 v102, v102
	v_add_f32_e32 v70, 1.0, v205
	v_rcp_f32_e32 v70, v70
	v_lshlrev_b32_e32 v107, 16, v103
	v_fmac_f32_e32 v107, v202, v72
	v_add_f32_e32 v72, 1.0, v102
	v_rcp_f32_e32 v72, v72
	v_mul_f32_e32 v70, v70, v204
	v_mul_f32_e32 v102, v70, v107
	v_and_b32_e32 v70, 0xffff0000, v103
	v_fmac_f32_e32 v70, v202, v73
	v_mul_f32_e32 v71, v72, v71
	s_waitcnt vmcnt(14)
	v_lshlrev_b32_e32 v72, 16, v98
	v_mul_f32_e32 v103, v71, v70
	v_mul_f32_e32 v70, 0xbfb8aa3b, v72
	v_exp_f32_e32 v73, v70
	v_and_b32_e32 v98, 0xffff0000, v98
	v_mul_f32_e32 v203, 0xbfb8aa3b, v98
	v_exp_f32_e32 v203, v203
	v_add_f32_e32 v73, 1.0, v73
	v_rcp_f32_e32 v73, v73
	v_lshlrev_b32_e32 v107, 16, v94
	v_fmac_f32_e32 v107, v202, v66
	v_and_b32_e32 v94, 0xffff0000, v94
	v_mul_f32_e32 v66, v73, v72
	v_lshlrev_b32_e32 v73, 16, v99
	v_mul_f32_e32 v66, v66, v107
	v_add_f32_e32 v72, 1.0, v203
	v_mul_f32_e32 v107, 0xbfb8aa3b, v73
	v_rcp_f32_e32 v72, v72
	v_exp_f32_e32 v107, v107
	v_fmac_f32_e32 v94, v202, v67
	v_cvt_pk_bf16_f32 v49, v60, v61
	v_mul_f32_e32 v67, v72, v98
	v_add_f32_e32 v72, 1.0, v107
	v_rcp_f32_e32 v72, v72
	v_mul_f32_e32 v67, v67, v94
	v_lshlrev_b32_e32 v94, 16, v95
	v_fmac_f32_e32 v94, v202, v68
	v_mul_f32_e32 v68, v72, v73
	v_and_b32_e32 v72, 0xffff0000, v99
	v_mul_f32_e32 v73, 0xbfb8aa3b, v72
	v_mul_f32_e32 v68, v68, v94
	v_and_b32_e32 v94, 0xffff0000, v95
	v_cvt_pk_bf16_f32 v50, v50, v51
	v_cvt_pk_bf16_f32 v51, v52, v53
	v_cvt_pk_bf16_f32 v52, v38, v39
	v_cvt_pk_bf16_f32 v53, v40, v41
	v_exp_f32_e32 v73, v73
	v_fmac_f32_e32 v94, v202, v69
	ds_write_b128 v128, v[46:49] offset:34816
	ds_write_b128 v128, v[50:53] offset:34832
	s_waitcnt lgkmcnt(0)
	s_barrier
	ds_read_b128 v[38:41], v129 offset:34816
	ds_read_b128 v[46:49], v129 offset:34880
	ds_read_b128 v[50:53], v129 offset:39168
	ds_read_b128 v[202:205], v129 offset:39232
	ds_read_b128 v[206:209], v129 offset:34944
	ds_read_b128 v[210:213], v129 offset:35008
	ds_read_b128 v[214:217], v129 offset:39296
	ds_read_b128 v[218:221], v129 offset:39360
	v_add_f32_e32 v69, 1.0, v73
	v_rcp_f32_e32 v69, v69
	v_cvt_pk_bf16_f32 v71, v106, v74
	v_cvt_pk_bf16_f32 v70, v102, v103
	v_cvt_pk_bf16_f32 v73, v66, v67
	s_nop 0
	v_mul_f32_e32 v58, v69, v72
	v_mul_f32_e32 v58, v58, v94
	v_cvt_pk_bf16_f32 v72, v68, v58
	s_waitcnt vmcnt(9)
	v_mul_f32_e32 v59, 0x3fb8aa3b, v222
	s_waitcnt lgkmcnt(7)
	v_mfma_f32_16x16x32_bf16 v[222:225], v[38:41], v[30:33], 0
	s_waitcnt vmcnt(5)
	v_lshlrev_b32_e32 v60, 16, v234
	v_mul_f32_e32 v61, 0xbfb8aa3b, v60
	v_exp_f32_e32 v61, v61
	s_waitcnt lgkmcnt(6)
	v_mfma_f32_16x16x32_bf16 v[222:225], v[46:49], v[22:25], v[222:225]
	v_and_b32_e32 v94, 0xffff0000, v234
	v_mul_f32_e32 v95, 0xbfb8aa3b, v94
	v_add_f32_e32 v61, 1.0, v61
	s_waitcnt lgkmcnt(3)
	v_mfma_f32_16x16x32_bf16 v[222:225], v[206:209], v[14:17], v[222:225]
	v_rcp_f32_e32 v61, v61
	v_exp_f32_e32 v95, v95
	v_exp_f32_e32 v59, v59
	s_waitcnt lgkmcnt(2)
	v_mfma_f32_16x16x32_bf16 v[222:225], v[210:213], v[6:9], v[222:225]
	v_mul_f32_e32 v60, v61, v60
	v_add_f32_e32 v61, 1.0, v95
	v_rcp_f32_e32 v61, v61
	v_lshlrev_b32_e32 v69, 16, v230
	v_and_b32_e32 v98, 0xffff0000, v235
	s_nop 2
	v_fmac_f32_e32 v69, v59, v222
	v_mul_f32_e32 v60, v60, v69
	v_and_b32_e32 v69, 0xffff0000, v230
	v_fmac_f32_e32 v69, v59, v223
	v_mul_f32_e32 v61, v61, v94
	v_mul_f32_e32 v61, v61, v69
	v_lshlrev_b32_e32 v69, 16, v235
	v_mul_f32_e32 v94, 0xbfb8aa3b, v69
	v_exp_f32_e32 v94, v94
	v_mul_f32_e32 v99, 0xbfb8aa3b, v98
	v_mfma_f32_16x16x32_bf16 v[226:229], v[50:53], v[30:33], 0
	v_exp_f32_e32 v99, v99
	v_add_f32_e32 v94, 1.0, v94
	v_rcp_f32_e32 v94, v94
	v_mfma_f32_16x16x32_bf16 v[38:41], v[38:41], v[26:29], 0
	v_lshlrev_b32_e32 v95, 16, v231
	v_fmac_f32_e32 v95, v59, v224
	s_or_b32 s18, s40, 7
	v_mfma_f32_16x16x32_bf16 v[50:53], v[50:53], v[26:29], 0
	s_or_b32 s16, s39, s18
	s_lshl_b64 s[16:17], s[16:17], 9
	s_add_u32 s16, s26, s16
	v_mfma_f32_16x16x32_bf16 v[38:41], v[46:49], v[18:21], v[38:41]
	s_addc_u32 s17, s27, s17
	s_lshl_b32 s20, s18, 7
	s_add_u32 s18, s24, s20
	v_mfma_f32_16x16x32_bf16 v[46:49], v[202:205], v[18:21], v[50:53]
	s_addc_u32 s19, s25, 0
	s_add_u32 s20, s60, s20
	s_addc_u32 s21, s61, 0
	v_mul_f32_e32 v50, v94, v69
	v_add_f32_e32 v94, 1.0, v99
	v_rcp_f32_e32 v94, v94
	v_mul_f32_e32 v69, v50, v95
	v_and_b32_e32 v95, 0xffff0000, v231
	v_fmac_f32_e32 v95, v59, v225
	v_mul_f32_e32 v94, v94, v98
	v_mul_f32_e32 v95, v94, v95
	v_mul_f32_e32 v94, v61, v61
	v_mfma_f32_16x16x32_bf16 v[38:41], v[206:209], v[10:13], v[38:41]
	v_fmac_f32_e32 v94, v60, v60
	v_fmac_f32_e32 v94, v69, v69
	v_fmac_f32_e32 v94, v95, v95
	v_mfma_f32_16x16x32_bf16 v[226:229], v[202:205], v[22:25], v[226:229]
	v_add_f32_e32 v98, v201, v94
	v_cvt_pk_bf16_f32 v94, v60, v61
	s_waitcnt vmcnt(4)
	v_lshlrev_b32_e32 v60, 16, v236
	s_waitcnt lgkmcnt(1)
	v_mfma_f32_16x16x32_bf16 v[46:49], v[214:217], v[10:13], v[46:49]
	v_cvt_pk_bf16_f32 v95, v69, v95
	v_cvt_pk_bf16_f32 v42, v42, v43
	v_cvt_pk_bf16_f32 v43, v44, v45
	v_mfma_f32_16x16x32_bf16 v[202:205], v[210:213], v[2:5], v[38:41]
	v_cvt_pk_bf16_f32 v44, v62, v63
	v_cvt_pk_bf16_f32 v45, v64, v65
	v_cvt_pk_bf16_f32 v54, v54, v55
	v_mfma_f32_16x16x32_bf16 v[50:53], v[214:217], v[14:17], v[226:229]
	v_cvt_pk_bf16_f32 v55, v56, v57
	s_nop 1
	v_mul_f32_e32 v38, 0xbfb8aa3b, v60
	v_exp_f32_e32 v61, v38
	s_waitcnt lgkmcnt(0)
	v_mfma_f32_16x16x32_bf16 v[38:41], v[218:221], v[2:5], v[46:49]
	v_cvt_pk_bf16_f32 v56, v34, v35
	v_cvt_pk_bf16_f32 v57, v36, v37
	v_mfma_f32_16x16x32_bf16 v[50:53], v[218:221], v[6:9], v[50:53]
	s_nop 1
	v_and_b32_e32 v48, 0xffff0000, v236
	v_mul_f32_e32 v49, 0xbfb8aa3b, v48
	v_add_f32_e32 v47, 1.0, v61
	v_exp_f32_e32 v49, v49
	v_rcp_f32_e32 v47, v47
	v_lshlrev_b32_e32 v46, 16, v232
	v_fmac_f32_e32 v46, v59, v50
	v_add_f32_e32 v49, 1.0, v49
	v_lshlrev_b32_e32 v50, 16, v237
	v_mul_f32_e32 v47, v47, v60
	v_rcp_f32_e32 v49, v49
	v_mul_f32_e32 v60, 0xbfb8aa3b, v50
	v_exp_f32_e32 v60, v60
	v_mul_f32_e32 v46, v47, v46
	v_and_b32_e32 v47, 0xffff0000, v232
	v_fmac_f32_e32 v47, v59, v51
	v_mul_f32_e32 v48, v49, v48
	v_and_b32_e32 v49, 0xffff0000, v237
	v_mul_f32_e32 v47, v48, v47
	v_add_f32_e32 v48, 1.0, v60
	v_mul_f32_e32 v51, 0xbfb8aa3b, v49
	v_rcp_f32_e32 v48, v48
	v_exp_f32_e32 v51, v51
	v_lshlrev_b32_e32 v60, 16, v233
	v_fmac_f32_e32 v60, v59, v52
	v_mul_f32_e32 v48, v48, v50
	v_add_f32_e32 v50, 1.0, v51
	v_rcp_f32_e32 v50, v50
	v_and_b32_e32 v51, 0xffff0000, v233
	v_mul_f32_e32 v48, v48, v60
	v_fmac_f32_e32 v51, v59, v53
	v_mul_f32_e32 v49, v50, v49
	v_mul_f32_e32 v50, v47, v47
	v_fmac_f32_e32 v50, v46, v46
	v_mul_f32_e32 v49, v49, v51
	v_fmac_f32_e32 v50, v48, v48
	v_fmac_f32_e32 v50, v49, v49
	v_add_f32_e32 v107, v98, v50
	v_cvt_pk_bf16_f32 v98, v46, v47
	v_mul_f32_e32 v46, 0x3fb8aa3b, v238
	v_exp_f32_e32 v201, v46
	s_waitcnt vmcnt(1)
	v_lshlrev_b32_e32 v46, 16, v104
	v_mul_f32_e32 v47, 0xbfb8aa3b, v46
	v_exp_f32_e32 v47, v47
	v_and_b32_e32 v60, 0xffff0000, v104
	v_cvt_pk_bf16_f32 v99, v48, v49
	v_mul_f32_e32 v49, 0xbfb8aa3b, v60
	v_add_f32_e32 v47, 1.0, v47
	v_rcp_f32_e32 v47, v47
	v_exp_f32_e32 v49, v49
	v_lshlrev_b32_e32 v48, 16, v100
	v_fmac_f32_e32 v48, v201, v202
	v_mul_f32_e32 v46, v47, v46
	v_mul_f32_e32 v59, v46, v48
	v_and_b32_e32 v61, 0xffff0000, v100
	v_add_f32_e32 v46, 1.0, v49
	v_lshlrev_b32_e32 v100, 16, v105
	v_rcp_f32_e32 v69, v46
	v_mul_f32_e32 v46, 0xbfb8aa3b, v100
	v_lshl_add_u64 v[48:49], s[18:19], 0, v[88:89]
	v_exp_f32_e32 v104, v46
	v_lshl_add_u64 v[46:47], s[16:17], 0, v[86:87]
	v_mov_b64_e32 v[50:51], s[20:21]
	v_lshl_add_u64 v[48:49], v[48:49], 0, v[76:77]
	v_mad_u64_u32 v[52:53], s[16:17], v82, s28, v[50:51]
	global_load_dword v218, v[46:47], off
	global_load_dwordx2 v[222:223], v[48:49], off
	global_load_dwordx2 v[224:225], v[48:49], off offset:32
	global_load_dword v230, v[46:47], off offset:64
	v_mad_u64_u32 v[48:49], s[16:17], v84, s28, v[50:51]
	v_add_u32_e32 v53, v81, v53
	v_lshl_add_u64 v[46:47], s[18:19], 0, v[90:91]
	v_add_u32_e32 v49, v79, v49
	v_lshl_add_u64 v[52:53], v[52:53], 0, v[76:77]
	v_lshl_add_u64 v[46:47], v[46:47], 0, v[76:77]
	v_lshl_add_u64 v[48:49], v[48:49], 0, v[76:77]
	global_load_dwordx2 v[226:227], v[52:53], off
	global_load_dwordx2 v[228:229], v[52:53], off offset:32
	global_load_dwordx2 v[50:51], v[46:47], off
	s_nop 0
	global_load_dwordx2 v[46:47], v[46:47], off offset:32
	s_nop 0
	global_load_dwordx2 v[52:53], v[48:49], off
	s_nop 0
	global_load_dwordx2 v[48:49], v[48:49], off offset:32
	v_mul_f32_e32 v60, v69, v60
	v_and_b32_e32 v69, 0xffff0000, v105
	v_mul_f32_e32 v77, 0xbfb8aa3b, v69
	v_exp_f32_e32 v77, v77
	v_fmac_f32_e32 v61, v201, v203
	v_mul_f32_e32 v60, v60, v61
	v_add_f32_e32 v61, 1.0, v104
	v_rcp_f32_e32 v61, v61
	v_add_f32_e32 v77, 1.0, v77
	v_rcp_f32_e32 v77, v77
	v_lshlrev_b32_e32 v86, 16, v101
	v_fmac_f32_e32 v86, v201, v204
	v_mul_f32_e32 v61, v61, v100
	v_mul_f32_e32 v61, v61, v86
	v_and_b32_e32 v86, 0xffff0000, v101
	v_fmac_f32_e32 v86, v201, v205
	v_mul_f32_e32 v69, v77, v69
	s_waitcnt vmcnt(10)
	v_lshlrev_b32_e32 v77, 16, v96
	v_mul_f32_e32 v69, v69, v86
	v_mul_f32_e32 v86, 0xbfb8aa3b, v77
	v_exp_f32_e32 v88, v86
	v_and_b32_e32 v90, 0xffff0000, v96
	v_mul_f32_e32 v91, 0xbfb8aa3b, v90
	v_exp_f32_e32 v91, v91
	v_add_f32_e32 v88, 1.0, v88
	v_rcp_f32_e32 v88, v88
	v_lshlrev_b32_e32 v89, 16, v92
	v_fmac_f32_e32 v89, v201, v38
	ds_write_b128 v128, v[42:45] offset:52224
	ds_write_b128 v128, v[54:57] offset:52240
	v_mul_f32_e32 v38, v88, v77
	v_lshlrev_b32_e32 v88, 16, v97
	v_mul_f32_e32 v38, v38, v89
	v_add_f32_e32 v77, 1.0, v91
	v_mul_f32_e32 v89, 0xbfb8aa3b, v88
	v_rcp_f32_e32 v77, v77
	v_exp_f32_e32 v89, v89
	v_and_b32_e32 v91, 0xffff0000, v92
	v_fmac_f32_e32 v91, v201, v39
	v_mul_f32_e32 v39, v77, v90
	v_add_f32_e32 v77, 1.0, v89
	v_rcp_f32_e32 v77, v77
	v_lshlrev_b32_e32 v89, 16, v93
	v_fmac_f32_e32 v89, v201, v40
	v_mul_f32_e32 v39, v39, v91
	v_mul_f32_e32 v40, v77, v88
	v_and_b32_e32 v77, 0xffff0000, v97
	v_mul_f32_e32 v88, 0xbfb8aa3b, v77
	v_exp_f32_e32 v88, v88
	v_mul_f32_e32 v40, v40, v89
	v_and_b32_e32 v89, 0xffff0000, v93
	s_waitcnt lgkmcnt(0)
	s_barrier
	ds_read_b128 v[42:45], v129 offset:52224
	ds_read_b128 v[54:57], v129 offset:52288
	ds_read_b128 v[62:65], v129 offset:56576
	ds_read_b128 v[90:93], v129 offset:56640
	ds_read_b128 v[202:205], v129 offset:52352
	ds_read_b128 v[206:209], v129 offset:52416
	ds_read_b128 v[210:213], v129 offset:56704
	ds_read_b128 v[214:217], v129 offset:56768
	v_fmac_f32_e32 v89, v201, v41
	v_add_f32_e32 v41, 1.0, v88
	v_rcp_f32_e32 v41, v41
	v_cvt_pk_bf16_f32 v87, v59, v60
	v_cvt_pk_bf16_f32 v86, v61, v69
	s_nop 0
	v_mul_f32_e32 v34, v41, v77
	v_mul_f32_e32 v34, v34, v89
	v_cvt_pk_bf16_f32 v89, v38, v39
	v_cvt_pk_bf16_f32 v88, v40, v34
	s_waitcnt vmcnt(9)
	v_mul_f32_e32 v35, 0x3fb8aa3b, v218
	s_waitcnt lgkmcnt(7)
	v_mfma_f32_16x16x32_bf16 v[218:221], v[42:45], v[30:33], 0
	s_waitcnt vmcnt(5)
	v_lshlrev_b32_e32 v36, 16, v226
	v_mul_f32_e32 v37, 0xbfb8aa3b, v36
	v_exp_f32_e32 v37, v37
	s_waitcnt lgkmcnt(5)
	v_mfma_f32_16x16x32_bf16 v[30:33], v[62:65], v[30:33], 0
	v_exp_f32_e32 v35, v35
	v_and_b32_e32 v77, 0xffff0000, v226
	v_add_f32_e32 v37, 1.0, v37
	v_mfma_f32_16x16x32_bf16 v[42:45], v[42:45], v[26:29], 0
	v_mul_f32_e32 v96, 0xbfb8aa3b, v77
	v_rcp_f32_e32 v37, v37
	v_exp_f32_e32 v96, v96
	v_mfma_f32_16x16x32_bf16 v[26:29], v[62:65], v[26:29], 0
	v_lshlrev_b32_e32 v41, 16, v222
	v_mul_f32_e32 v36, v37, v36
	v_add_f32_e32 v37, 1.0, v96
	v_mfma_f32_16x16x32_bf16 v[218:221], v[54:57], v[22:25], v[218:221]
	v_rcp_f32_e32 v37, v37
	v_lshlrev_b32_e32 v63, 16, v223
	v_mul_f32_e32 v37, v37, v77
	s_waitcnt lgkmcnt(4)
	v_mfma_f32_16x16x32_bf16 v[22:25], v[90:93], v[22:25], v[30:33]
	v_mfma_f32_16x16x32_bf16 v[30:33], v[54:57], v[18:21], v[42:45]
	s_nop 2
	v_and_b32_e32 v43, 0xffff0000, v227
	v_mul_f32_e32 v44, 0xbfb8aa3b, v43
	v_mfma_f32_16x16x32_bf16 v[18:21], v[90:93], v[18:21], v[26:29]
	s_nop 2
	v_exp_f32_e32 v26, v44
	s_waitcnt lgkmcnt(3)
	v_mfma_f32_16x16x32_bf16 v[218:221], v[202:205], v[14:17], v[218:221]
	v_and_b32_e32 v28, 0xffff0000, v223
	s_waitcnt lgkmcnt(1)
	v_mfma_f32_16x16x32_bf16 v[14:17], v[210:213], v[14:17], v[22:25]
	s_nop 2
	v_add_f32_e32 v22, 1.0, v26
	v_rcp_f32_e32 v26, v22
	v_mfma_f32_16x16x32_bf16 v[22:25], v[202:205], v[10:13], v[30:33]
	v_mul_f32_e32 v26, v26, v43
	v_mfma_f32_16x16x32_bf16 v[10:13], v[210:213], v[10:13], v[18:21]
	s_waitcnt vmcnt(4)
	s_nop 1
	v_lshlrev_b32_e32 v19, 16, v228
	v_mul_f32_e32 v20, 0xbfb8aa3b, v19
	v_exp_f32_e32 v20, v20
	v_mfma_f32_16x16x32_bf16 v[218:221], v[206:209], v[6:9], v[218:221]
	s_waitcnt lgkmcnt(0)
	v_mfma_f32_16x16x32_bf16 v[6:9], v[214:217], v[6:9], v[14:17]
	v_mfma_f32_16x16x32_bf16 v[14:17], v[206:209], v[2:5], v[22:25]
	s_nop 4
	v_fmac_f32_e32 v41, v35, v218
	v_mul_f32_e32 v36, v36, v41
	v_and_b32_e32 v41, 0xffff0000, v222
	v_mfma_f32_16x16x32_bf16 v[10:13], v[214:217], v[2:5], v[10:13]
	v_and_b32_e32 v4, 0xffff0000, v228
	v_mul_f32_e32 v5, 0xbfb8aa3b, v4
	v_add_f32_e32 v3, 1.0, v20
	v_exp_f32_e32 v5, v5
	v_rcp_f32_e32 v3, v3
	v_lshlrev_b32_e32 v2, 16, v224
	v_fmac_f32_e32 v2, v35, v6
	v_add_f32_e32 v5, 1.0, v5
	v_lshlrev_b32_e32 v6, 16, v229
	v_mul_f32_e32 v3, v3, v19
	v_rcp_f32_e32 v5, v5
	v_mul_f32_e32 v19, 0xbfb8aa3b, v6
	v_exp_f32_e32 v19, v19
	v_mul_f32_e32 v2, v3, v2
	v_and_b32_e32 v3, 0xffff0000, v224
	v_fmac_f32_e32 v3, v35, v7
	v_mul_f32_e32 v4, v5, v4
	v_and_b32_e32 v5, 0xffff0000, v229
	v_mul_f32_e32 v3, v4, v3
	v_add_f32_e32 v4, 1.0, v19
	v_mul_f32_e32 v7, 0xbfb8aa3b, v5
	v_rcp_f32_e32 v4, v4
	v_exp_f32_e32 v7, v7
	v_fmac_f32_e32 v41, v35, v219
	v_mul_f32_e32 v37, v37, v41
	v_lshlrev_b32_e32 v41, 16, v227
	v_mul_f32_e32 v62, 0xbfb8aa3b, v41
	v_exp_f32_e32 v62, v62
	v_mul_f32_e32 v4, v4, v6
	v_add_f32_e32 v6, 1.0, v7
	v_rcp_f32_e32 v6, v6
	v_add_f32_e32 v62, 1.0, v62
	v_rcp_f32_e32 v42, v62
	v_and_b32_e32 v7, 0xffff0000, v225
	v_mul_f32_e32 v5, v6, v5
	v_mul_f32_e32 v6, v3, v3
	v_fmac_f32_e32 v6, v2, v2
	v_cvt_pk_bf16_f32 v101, v2, v3
	v_mul_f32_e32 v2, 0x3fb8aa3b, v230
	v_fmac_f32_e32 v7, v35, v9
	v_exp_f32_e32 v9, v2
	s_waitcnt vmcnt(1)
	v_lshlrev_b32_e32 v2, 16, v52
	v_mul_f32_e32 v3, 0xbfb8aa3b, v2
	v_fmac_f32_e32 v63, v35, v220
	v_mul_f32_e32 v27, v42, v41
	v_mul_f32_e32 v18, v37, v37
	v_lshlrev_b32_e32 v19, 16, v225
	v_exp_f32_e32 v3, v3
	v_mul_f32_e32 v27, v27, v63
	v_fmac_f32_e32 v28, v35, v221
	v_fmac_f32_e32 v18, v36, v36
	v_fmac_f32_e32 v19, v35, v8
	v_mul_f32_e32 v26, v26, v28
	v_fmac_f32_e32 v18, v27, v27
	v_mul_f32_e32 v4, v4, v19
	v_fmac_f32_e32 v18, v26, v26
	v_mul_f32_e32 v5, v5, v7
	v_fmac_f32_e32 v6, v4, v4
	v_add_f32_e32 v18, v107, v18
	v_fmac_f32_e32 v6, v5, v5
	v_cvt_pk_bf16_f32 v100, v4, v5
	v_add_f32_e32 v3, 1.0, v3
	v_and_b32_e32 v5, 0xffff0000, v52
	v_add_f32_e32 v18, v18, v6
	v_rcp_f32_e32 v3, v3
	v_mul_f32_e32 v6, 0xbfb8aa3b, v5
	v_exp_f32_e32 v6, v6
	v_lshlrev_b32_e32 v4, 16, v50
	v_fmac_f32_e32 v4, v9, v14
	v_mul_f32_e32 v2, v3, v2
	v_mul_f32_e32 v2, v2, v4
	v_add_f32_e32 v4, 1.0, v6
	v_lshlrev_b32_e32 v6, 16, v53
	v_rcp_f32_e32 v4, v4
	v_mul_f32_e32 v7, 0xbfb8aa3b, v6
	v_exp_f32_e32 v7, v7
	v_and_b32_e32 v3, 0xffff0000, v50
	v_fmac_f32_e32 v3, v9, v15
	v_mul_f32_e32 v4, v4, v5
	v_and_b32_e32 v5, 0xffff0000, v53
	v_mul_f32_e32 v3, v4, v3
	v_add_f32_e32 v4, 1.0, v7
	v_mul_f32_e32 v7, 0xbfb8aa3b, v5
	v_rcp_f32_e32 v4, v4
	v_exp_f32_e32 v7, v7
	v_lshlrev_b32_e32 v8, 16, v51
	v_fmac_f32_e32 v8, v9, v16
	v_mul_f32_e32 v4, v4, v6
	v_add_f32_e32 v6, 1.0, v7
	v_rcp_f32_e32 v6, v6
	v_and_b32_e32 v7, 0xffff0000, v51
	v_fmac_f32_e32 v7, v9, v17
	v_mul_f32_e32 v4, v4, v8
	v_mul_f32_e32 v5, v6, v5
	s_waitcnt vmcnt(0)
	v_lshlrev_b32_e32 v6, 16, v48
	v_mul_f32_e32 v5, v5, v7
	v_mul_f32_e32 v7, 0xbfb8aa3b, v6
	v_exp_f32_e32 v7, v7
	v_lshlrev_b32_e32 v8, 16, v46
	v_fmac_f32_e32 v8, v9, v10
	v_and_b32_e32 v10, 0xffff0000, v48
	v_add_f32_e32 v7, 1.0, v7
	v_rcp_f32_e32 v7, v7
	v_mul_f32_e32 v14, 0xbfb8aa3b, v10
	v_exp_f32_e32 v14, v14
	v_lshlrev_b32_e32 v16, 2, v147
	v_mul_f32_e32 v6, v7, v6
	v_mul_f32_e32 v6, v6, v8
	v_add_f32_e32 v8, 1.0, v14
	v_rcp_f32_e32 v8, v8
	v_and_b32_e32 v7, 0xffff0000, v46
	v_fmac_f32_e32 v7, v9, v11
	v_lshlrev_b32_e32 v14, 16, v49
	v_mul_f32_e32 v8, v8, v10
	v_and_b32_e32 v10, 0xffff0000, v49
	v_mul_f32_e32 v11, 0xbfb8aa3b, v10
	v_exp_f32_e32 v11, v11
	v_mul_f32_e32 v15, 0xbfb8aa3b, v14
	v_exp_f32_e32 v15, v15
	v_mul_f32_e32 v7, v8, v7
	v_add_f32_e32 v11, 1.0, v11
	v_rcp_f32_e32 v11, v11
	v_add_f32_e32 v8, 1.0, v15
	v_lshlrev_b32_e32 v15, 16, v47
	v_fmac_f32_e32 v15, v9, v12
	v_and_b32_e32 v12, 0xffff0000, v47
	v_fmac_f32_e32 v12, v9, v13
	v_mul_f32_e32 v9, v11, v10
	v_and_b32_e32 v11, 64, v144
	v_xor_b32_e32 v10, 16, v144
	v_add_u32_e32 v11, 64, v11
	v_cmp_lt_i32_e32 vcc, v10, v11
	v_rcp_f32_e32 v8, v8
	v_mul_f32_e32 v9, v9, v12
	v_cndmask_b32_e32 v10, v144, v10, vcc
	v_lshlrev_b32_e32 v10, 2, v10
	ds_bpermute_b32 v13, v10, v18
	v_xor_b32_e32 v12, 32, v144
	v_cmp_lt_i32_e32 vcc, v12, v11
	v_mul_f32_e32 v8, v8, v14
	v_mul_f32_e32 v8, v8, v15
	v_cndmask_b32_e32 v11, v144, v12, vcc
	v_lshlrev_b32_e32 v12, 2, v11
	s_waitcnt lgkmcnt(0)
	v_add_f32_e32 v13, v18, v13
	ds_bpermute_b32 v14, v12, v13
	v_lshl_add_u32 v11, v112, 9, s36
	v_and_b32_e32 v15, 0xffffff80, v146
	v_cmp_eq_u32_e32 vcc, 0, v148
	v_add3_u32 v11, v11, v15, v16
	v_cvt_pk_bf16_f32 v96, v36, v37
	v_cvt_pk_bf16_f32 v97, v27, v26
	v_cvt_pk_bf16_f32 v90, v2, v3
	v_cvt_pk_bf16_f32 v91, v4, v5
	v_cvt_pk_bf16_f32 v93, v6, v7
	v_cvt_pk_bf16_f32 v92, v8, v9
	s_and_saveexec_b64 s[16:17], vcc
	s_cbranch_execz .LBB0_546
	s_waitcnt lgkmcnt(0)
	v_add_f32_e32 v13, v13, v14
	ds_write_b32 v11, v13
